# plus: LDS-DMA loads in GU1/GU2/in-proj K-loops use SGPR-base + 32-bit VGPR offset form (no per-load 64-bit VALU address add)
# speedup vs baseline: 1.0128x; 1.0021x over previous
.Lrb0_skip:
	s_add_u32 s48, s46, 0xfffc0080
	s_addc_u32 s49, s47, -1
	s_add_i32 s63, 0, 0x10000
	s_cmp_eq_u32 s62, 12
	s_cselect_b32 s51, s39, s49
	s_cselect_b32 s50, s58, s48
	v_add_u32_e32 v0, s63, v144
	s_cselect_b32 s49, s23, s61
	s_cselect_b32 s48, s59, s60
	s_add_i32 s66, 0, 0x14000
	ds_read_b128 v[146:149], v0
	ds_read_b128 v[150:153], v0 offset:1024
	ds_read_b128 v[154:157], v0 offset:2048
	ds_read_b128 v[158:161], v0 offset:3072
	v_add_u32_e32 v0, s66, v144
	ds_read_b128 v[162:165], v0
	ds_read_b128 v[166:169], v0 offset:1024
	ds_read_b128 v[170:173], v0 offset:2048
	ds_read_b128 v[174:177], v0 offset:3072
	s_add_i32 m0, s5, 0xc000
	ds_read_b128 v[178:181], v145
	ds_read_b128 v[182:185], v145 offset:1024
	ds_read_b128 v[204:207], v145 offset:2048
	ds_read_b128 v[208:211], v145 offset:3072
	ds_read_b128 v[212:215], v145 offset:4096
	ds_read_b128 v[216:219], v145 offset:5120
	ds_read_b128 v[220:223], v145 offset:6144
	ds_read_b128 v[224:227], v145 offset:7168
	global_load_lds_dwordx4 v138, s[46:47]
	s_add_i32 m0, s5, 0xe000
	s_nop 0
	global_load_lds_dwordx4 v140, s[46:47]
	s_waitcnt vmcnt(8)
	s_waitcnt lgkmcnt(0)
	s_setprio 1
	s_barrier
	v_mfma_f32_16x16x32_bf16 v[118:121], v[146:149], v[178:181], 0
	v_mfma_f32_16x16x32_bf16 v[114:117], v[154:157], v[178:181], 0
	v_mfma_f32_16x16x32_bf16 v[110:113], v[146:149], v[204:207], 0
	v_mfma_f32_16x16x32_bf16 v[102:105], v[154:157], v[204:207], 0
	v_mfma_f32_16x16x32_bf16 v[94:97], v[146:149], v[212:215], 0
	v_mfma_f32_16x16x32_bf16 v[86:89], v[154:157], v[212:215], 0
	v_mfma_f32_16x16x32_bf16 v[78:81], v[146:149], v[220:223], 0
	v_mfma_f32_16x16x32_bf16 v[70:73], v[154:157], v[220:223], 0
	v_mfma_f32_16x16x32_bf16 v[118:121], v[150:153], v[182:185], v[118:121]
	v_mfma_f32_16x16x32_bf16 v[114:117], v[158:161], v[182:185], v[114:117]
	v_mfma_f32_16x16x32_bf16 v[110:113], v[150:153], v[208:211], v[110:113]
	v_mfma_f32_16x16x32_bf16 v[102:105], v[158:161], v[208:211], v[102:105]
	v_mfma_f32_16x16x32_bf16 v[94:97], v[150:153], v[216:219], v[94:97]
	v_mfma_f32_16x16x32_bf16 v[86:89], v[158:161], v[216:219], v[86:89]
	v_mfma_f32_16x16x32_bf16 v[78:81], v[150:153], v[224:227], v[78:81]
	v_mfma_f32_16x16x32_bf16 v[70:73], v[158:161], v[224:227], v[70:73]
	v_mfma_f32_16x16x32_bf16 v[126:129], v[162:165], v[178:181], 0
	v_mfma_f32_16x16x32_bf16 v[122:125], v[170:173], v[178:181], 0
	v_mfma_f32_16x16x32_bf16 v[106:109], v[162:165], v[204:207], 0
	v_mfma_f32_16x16x32_bf16 v[98:101], v[170:173], v[204:207], 0
	v_mfma_f32_16x16x32_bf16 v[90:93], v[162:165], v[212:215], 0
	v_mfma_f32_16x16x32_bf16 v[82:85], v[170:173], v[212:215], 0
	v_mfma_f32_16x16x32_bf16 v[74:77], v[162:165], v[220:223], 0
	v_mfma_f32_16x16x32_bf16 v[66:69], v[170:173], v[220:223], 0
	v_mfma_f32_16x16x32_bf16 v[126:129], v[166:169], v[182:185], v[126:129]
	v_mfma_f32_16x16x32_bf16 v[122:125], v[174:177], v[182:185], v[122:125]
	v_mfma_f32_16x16x32_bf16 v[106:109], v[166:169], v[208:211], v[106:109]
	v_mfma_f32_16x16x32_bf16 v[98:101], v[174:177], v[208:211], v[98:101]
	v_mfma_f32_16x16x32_bf16 v[90:93], v[166:169], v[216:219], v[90:93]
	v_mfma_f32_16x16x32_bf16 v[82:85], v[174:177], v[216:219], v[82:85]
	v_mfma_f32_16x16x32_bf16 v[74:77], v[166:169], v[224:227], v[74:77]
	v_mfma_f32_16x16x32_bf16 v[66:69], v[174:177], v[224:227], v[66:69]
	s_barrier
	s_setprio 0
	s_add_i32 s63, s63, s4
	s_mov_b32 m0, s63
	ds_read_b128 v[178:181], v145 offset:16384
	ds_read_b128 v[182:185], v145 offset:17408
	ds_read_b128 v[204:207], v145 offset:18432
	ds_read_b128 v[208:211], v145 offset:19456
	ds_read_b128 v[212:215], v145 offset:20480
	ds_read_b128 v[216:219], v145 offset:21504
	ds_read_b128 v[220:223], v145 offset:22528
	ds_read_b128 v[224:227], v145 offset:23552
	global_load_lds_dwordx4 v134, s[48:49]
	s_add_i32 m0, s63, 0x2000
	s_add_u32 s64, s48, 0x40000
	s_addc_u32 s65, s49, 0
	s_add_i32 s63, s66, s4
	global_load_lds_dwordx4 v130, s[48:49]
	s_mov_b32 m0, s63
	s_nop 0
	global_load_lds_dwordx4 v134, s[64:65]
	s_add_i32 m0, s63, 0x2000
	s_nop 0
	global_load_lds_dwordx4 v130, s[64:65]
	s_mov_b32 m0, s5
	s_nop 0
	global_load_lds_dwordx4 v136, s[50:51]
	s_mov_b32 m0, s6
	s_nop 0
	global_load_lds_dwordx4 v132, s[50:51]
	s_waitcnt vmcnt(8)
	s_waitcnt lgkmcnt(0)
	s_setprio 1
	s_barrier
	v_mfma_f32_16x16x32_bf16 v[62:65], v[146:149], v[178:181], 0
	v_mfma_f32_16x16x32_bf16 v[54:57], v[154:157], v[178:181], 0
	v_mfma_f32_16x16x32_bf16 v[46:49], v[146:149], v[204:207], 0
	v_mfma_f32_16x16x32_bf16 v[38:41], v[154:157], v[204:207], 0
	v_mfma_f32_16x16x32_bf16 v[30:33], v[146:149], v[212:215], 0
	v_mfma_f32_16x16x32_bf16 v[22:25], v[154:157], v[212:215], 0
	v_mfma_f32_16x16x32_bf16 v[14:17], v[146:149], v[220:223], 0
	v_mfma_f32_16x16x32_bf16 v[6:9], v[154:157], v[220:223], 0
	v_mfma_f32_16x16x32_bf16 v[62:65], v[150:153], v[182:185], v[62:65]
	v_mfma_f32_16x16x32_bf16 v[54:57], v[158:161], v[182:185], v[54:57]
	v_mfma_f32_16x16x32_bf16 v[46:49], v[150:153], v[208:211], v[46:49]
	v_mfma_f32_16x16x32_bf16 v[38:41], v[158:161], v[208:211], v[38:41]
	v_mfma_f32_16x16x32_bf16 v[30:33], v[150:153], v[216:219], v[30:33]
	v_mfma_f32_16x16x32_bf16 v[22:25], v[158:161], v[216:219], v[22:25]
	v_mfma_f32_16x16x32_bf16 v[14:17], v[150:153], v[224:227], v[14:17]
	v_mfma_f32_16x16x32_bf16 v[6:9], v[158:161], v[224:227], v[6:9]
	v_mfma_f32_16x16x32_bf16 v[58:61], v[162:165], v[178:181], 0
	v_mfma_f32_16x16x32_bf16 v[50:53], v[170:173], v[178:181], 0
	v_mfma_f32_16x16x32_bf16 v[42:45], v[162:165], v[204:207], 0
	v_mfma_f32_16x16x32_bf16 v[34:37], v[170:173], v[204:207], 0
	v_mfma_f32_16x16x32_bf16 v[26:29], v[162:165], v[212:215], 0
	v_mfma_f32_16x16x32_bf16 v[18:21], v[170:173], v[212:215], 0
	v_mfma_f32_16x16x32_bf16 v[10:13], v[162:165], v[220:223], 0
	v_mfma_f32_16x16x32_bf16 v[2:5], v[170:173], v[220:223], 0
	v_mfma_f32_16x16x32_bf16 v[58:61], v[166:169], v[182:185], v[58:61]
	v_mfma_f32_16x16x32_bf16 v[50:53], v[174:177], v[182:185], v[50:53]
	v_mfma_f32_16x16x32_bf16 v[42:45], v[166:169], v[208:211], v[42:45]
	v_mfma_f32_16x16x32_bf16 v[34:37], v[174:177], v[208:211], v[34:37]
	v_mfma_f32_16x16x32_bf16 v[26:29], v[166:169], v[216:219], v[26:29]
	v_mfma_f32_16x16x32_bf16 v[18:21], v[174:177], v[216:219], v[18:21]
	v_mfma_f32_16x16x32_bf16 v[10:13], v[166:169], v[224:227], v[10:13]
	v_mfma_f32_16x16x32_bf16 v[2:5], v[174:177], v[224:227], v[2:5]
	s_barrier
	s_setprio 0
	s_add_i32 s63, 0, 0x18000
	v_add_u32_e32 v0, s63, v144
	s_add_i32 s64, 0, 0x1c000
	ds_read_b128 v[146:149], v0
	ds_read_b128 v[150:153], v0 offset:1024
	ds_read_b128 v[154:157], v0 offset:2048
	ds_read_b128 v[158:161], v0 offset:3072
	v_add_u32_e32 v0, s64, v144
	ds_read_b128 v[162:165], v0
	ds_read_b128 v[166:169], v0 offset:1024
	ds_read_b128 v[170:173], v0 offset:2048
	ds_read_b128 v[174:177], v0 offset:3072
	s_add_u32 s50, s50, 0x40000
	s_addc_u32 s51, s51, 0
	s_mov_b32 m0, s7
	ds_read_b128 v[178:181], v145 offset:32768
	ds_read_b128 v[182:185], v145 offset:33792
	ds_read_b128 v[204:207], v145 offset:34816
	ds_read_b128 v[208:211], v145 offset:35840
	ds_read_b128 v[212:215], v145 offset:36864
	ds_read_b128 v[216:219], v145 offset:37888
	ds_read_b128 v[220:223], v145 offset:38912
	ds_read_b128 v[224:227], v145 offset:39936
	global_load_lds_dwordx4 v136, s[50:51]
	s_mov_b32 m0, s52
	s_nop 0
	global_load_lds_dwordx4 v132, s[50:51]
	s_waitcnt vmcnt(8)
	s_waitcnt lgkmcnt(0)
	s_setprio 1
	s_barrier
	v_mfma_f32_16x16x32_bf16 v[118:121], v[146:149], v[178:181], v[118:121]
	v_mfma_f32_16x16x32_bf16 v[114:117], v[154:157], v[178:181], v[114:117]
	v_mfma_f32_16x16x32_bf16 v[110:113], v[146:149], v[204:207], v[110:113]
	v_mfma_f32_16x16x32_bf16 v[102:105], v[154:157], v[204:207], v[102:105]
	v_mfma_f32_16x16x32_bf16 v[94:97], v[146:149], v[212:215], v[94:97]
	v_mfma_f32_16x16x32_bf16 v[86:89], v[154:157], v[212:215], v[86:89]
	v_mfma_f32_16x16x32_bf16 v[78:81], v[146:149], v[220:223], v[78:81]
	v_mfma_f32_16x16x32_bf16 v[70:73], v[154:157], v[220:223], v[70:73]
	v_mfma_f32_16x16x32_bf16 v[118:121], v[150:153], v[182:185], v[118:121]
	v_mfma_f32_16x16x32_bf16 v[114:117], v[158:161], v[182:185], v[114:117]
	v_mfma_f32_16x16x32_bf16 v[110:113], v[150:153], v[208:211], v[110:113]
	v_mfma_f32_16x16x32_bf16 v[102:105], v[158:161], v[208:211], v[102:105]
	v_mfma_f32_16x16x32_bf16 v[94:97], v[150:153], v[216:219], v[94:97]
	v_mfma_f32_16x16x32_bf16 v[86:89], v[158:161], v[216:219], v[86:89]
	v_mfma_f32_16x16x32_bf16 v[78:81], v[150:153], v[224:227], v[78:81]
	v_mfma_f32_16x16x32_bf16 v[70:73], v[158:161], v[224:227], v[70:73]
	v_mfma_f32_16x16x32_bf16 v[126:129], v[162:165], v[178:181], v[126:129]
	v_mfma_f32_16x16x32_bf16 v[122:125], v[170:173], v[178:181], v[122:125]
	v_mfma_f32_16x16x32_bf16 v[106:109], v[162:165], v[204:207], v[106:109]
	v_mfma_f32_16x16x32_bf16 v[98:101], v[170:173], v[204:207], v[98:101]
	v_mfma_f32_16x16x32_bf16 v[90:93], v[162:165], v[212:215], v[90:93]
	v_mfma_f32_16x16x32_bf16 v[82:85], v[170:173], v[212:215], v[82:85]
	v_mfma_f32_16x16x32_bf16 v[74:77], v[162:165], v[220:223], v[74:77]
	v_mfma_f32_16x16x32_bf16 v[66:69], v[170:173], v[220:223], v[66:69]
	v_mfma_f32_16x16x32_bf16 v[126:129], v[166:169], v[182:185], v[126:129]
	v_mfma_f32_16x16x32_bf16 v[122:125], v[174:177], v[182:185], v[122:125]
	v_mfma_f32_16x16x32_bf16 v[106:109], v[166:169], v[208:211], v[106:109]
	v_mfma_f32_16x16x32_bf16 v[98:101], v[174:177], v[208:211], v[98:101]
	v_mfma_f32_16x16x32_bf16 v[90:93], v[166:169], v[216:219], v[90:93]
	v_mfma_f32_16x16x32_bf16 v[82:85], v[174:177], v[216:219], v[82:85]
	v_mfma_f32_16x16x32_bf16 v[74:77], v[166:169], v[224:227], v[74:77]
	v_mfma_f32_16x16x32_bf16 v[66:69], v[174:177], v[224:227], v[66:69]
	s_barrier
	s_setprio 0
	s_add_i32 s65, s63, s4
	s_add_u32 s48, s48, 0x80
	s_addc_u32 s49, s49, 0
	s_mov_b32 m0, s65
	ds_read_b128 v[178:181], v145 offset:49152
	ds_read_b128 v[182:185], v145 offset:50176
	ds_read_b128 v[204:207], v145 offset:51200
	ds_read_b128 v[208:211], v145 offset:52224
	ds_read_b128 v[212:215], v145 offset:53248
	ds_read_b128 v[216:219], v145 offset:54272
	ds_read_b128 v[220:223], v145 offset:55296
	ds_read_b128 v[224:227], v145 offset:56320
	global_load_lds_dwordx4 v134, s[48:49]
	s_add_i32 m0, s65, 0x2000
	s_add_i32 s65, s64, s4
	global_load_lds_dwordx4 v130, s[48:49]
	s_add_u32 s48, s48, 0x40000
	s_addc_u32 s49, s49, 0
	s_mov_b32 m0, s65
	s_sub_u32 s50, s50, 0x3ff80
	global_load_lds_dwordx4 v134, s[48:49]
	s_subb_u32 s51, s51, 0
	s_add_i32 m0, s65, 0x2000
	s_nop 0
	global_load_lds_dwordx4 v130, s[48:49]
	s_mov_b32 m0, s55
	s_nop 0
	global_load_lds_dwordx4 v136, s[50:51]
	s_mov_b32 m0, s56
	s_nop 0
	global_load_lds_dwordx4 v132, s[50:51]
	s_waitcnt vmcnt(8)
	s_waitcnt lgkmcnt(0)
	s_setprio 1
	s_barrier
	v_mfma_f32_16x16x32_bf16 v[62:65], v[146:149], v[178:181], v[62:65]
	v_mfma_f32_16x16x32_bf16 v[54:57], v[154:157], v[178:181], v[54:57]
	v_mfma_f32_16x16x32_bf16 v[46:49], v[146:149], v[204:207], v[46:49]
	v_mfma_f32_16x16x32_bf16 v[38:41], v[154:157], v[204:207], v[38:41]
	v_mfma_f32_16x16x32_bf16 v[30:33], v[146:149], v[212:215], v[30:33]
	v_mfma_f32_16x16x32_bf16 v[22:25], v[154:157], v[212:215], v[22:25]
	v_mfma_f32_16x16x32_bf16 v[14:17], v[146:149], v[220:223], v[14:17]
	v_mfma_f32_16x16x32_bf16 v[6:9], v[154:157], v[220:223], v[6:9]
	v_mfma_f32_16x16x32_bf16 v[62:65], v[150:153], v[182:185], v[62:65]
	v_mfma_f32_16x16x32_bf16 v[54:57], v[158:161], v[182:185], v[54:57]
	v_mfma_f32_16x16x32_bf16 v[46:49], v[150:153], v[208:211], v[46:49]
	v_mfma_f32_16x16x32_bf16 v[38:41], v[158:161], v[208:211], v[38:41]
	v_mfma_f32_16x16x32_bf16 v[30:33], v[150:153], v[216:219], v[30:33]
	v_mfma_f32_16x16x32_bf16 v[22:25], v[158:161], v[216:219], v[22:25]
	v_mfma_f32_16x16x32_bf16 v[14:17], v[150:153], v[224:227], v[14:17]
	v_mfma_f32_16x16x32_bf16 v[6:9], v[158:161], v[224:227], v[6:9]
	v_mfma_f32_16x16x32_bf16 v[58:61], v[162:165], v[178:181], v[58:61]
	v_mfma_f32_16x16x32_bf16 v[50:53], v[170:173], v[178:181], v[50:53]
	v_mfma_f32_16x16x32_bf16 v[42:45], v[162:165], v[204:207], v[42:45]
	v_mfma_f32_16x16x32_bf16 v[34:37], v[170:173], v[204:207], v[34:37]
	v_mfma_f32_16x16x32_bf16 v[26:29], v[162:165], v[212:215], v[26:29]
	v_mfma_f32_16x16x32_bf16 v[18:21], v[170:173], v[212:215], v[18:21]
	v_mfma_f32_16x16x32_bf16 v[10:13], v[162:165], v[220:223], v[10:13]
	v_mfma_f32_16x16x32_bf16 v[2:5], v[170:173], v[220:223], v[2:5]
	v_mfma_f32_16x16x32_bf16 v[58:61], v[166:169], v[182:185], v[58:61]
	v_mfma_f32_16x16x32_bf16 v[50:53], v[174:177], v[182:185], v[50:53]
	v_mfma_f32_16x16x32_bf16 v[42:45], v[166:169], v[208:211], v[42:45]
	v_mfma_f32_16x16x32_bf16 v[34:37], v[174:177], v[208:211], v[34:37]
	v_mfma_f32_16x16x32_bf16 v[26:29], v[166:169], v[216:219], v[26:29]
	v_mfma_f32_16x16x32_bf16 v[18:21], v[174:177], v[216:219], v[18:21]
	v_mfma_f32_16x16x32_bf16 v[10:13], v[166:169], v[224:227], v[10:13]
	v_mfma_f32_16x16x32_bf16 v[2:5], v[174:177], v[224:227], v[2:5]
	s_barrier
	s_setprio 0
	s_add_i32 s62, s62, 2
	s_add_u32 s46, s46, 0x100
	s_addc_u32 s47, s47, 0
	s_add_u32 s60, s60, 0x100
	s_addc_u32 s61, s61, 0
	s_cmp_gt_u32 s62, 13
.LBB0_229:
	s_add_u32 s48, s46, 0xfffc0080
	s_addc_u32 s49, s47, -1
	s_add_i32 s63, 0, 0x10000
	s_cmp_eq_u32 s62, 12
	s_cselect_b32 s51, s39, s49
	s_cselect_b32 s50, s58, s48
	v_add_u32_e32 v0, s63, v144
	s_cselect_b32 s49, s23, s61
	s_cselect_b32 s48, s59, s60
	s_add_i32 s66, 0, 0x14000
	ds_read_b128 v[146:149], v0
	ds_read_b128 v[150:153], v0 offset:1024
	ds_read_b128 v[154:157], v0 offset:2048
	ds_read_b128 v[158:161], v0 offset:3072
	v_add_u32_e32 v0, s66, v144
	ds_read_b128 v[162:165], v0
	ds_read_b128 v[166:169], v0 offset:1024
	ds_read_b128 v[170:173], v0 offset:2048
	ds_read_b128 v[174:177], v0 offset:3072
	s_add_i32 m0, s5, 0xc000
	ds_read_b128 v[178:181], v145
	ds_read_b128 v[182:185], v145 offset:1024
	ds_read_b128 v[204:207], v145 offset:2048
	ds_read_b128 v[208:211], v145 offset:3072
	ds_read_b128 v[212:215], v145 offset:4096
	ds_read_b128 v[216:219], v145 offset:5120
	ds_read_b128 v[220:223], v145 offset:6144
	ds_read_b128 v[224:227], v145 offset:7168
	global_load_lds_dwordx4 v138, s[46:47]
	s_add_i32 m0, s5, 0xe000
	s_nop 0
	global_load_lds_dwordx4 v140, s[46:47]
	s_waitcnt vmcnt(8)
	s_waitcnt lgkmcnt(0)
	s_setprio 1
	s_barrier
	v_mfma_f32_16x16x32_bf16 v[118:121], v[146:149], v[178:181], v[118:121]
	v_mfma_f32_16x16x32_bf16 v[114:117], v[154:157], v[178:181], v[114:117]
	v_mfma_f32_16x16x32_bf16 v[110:113], v[146:149], v[204:207], v[110:113]
	v_mfma_f32_16x16x32_bf16 v[102:105], v[154:157], v[204:207], v[102:105]
	v_mfma_f32_16x16x32_bf16 v[94:97], v[146:149], v[212:215], v[94:97]
	v_mfma_f32_16x16x32_bf16 v[86:89], v[154:157], v[212:215], v[86:89]
	v_mfma_f32_16x16x32_bf16 v[78:81], v[146:149], v[220:223], v[78:81]
	v_mfma_f32_16x16x32_bf16 v[70:73], v[154:157], v[220:223], v[70:73]
	v_mfma_f32_16x16x32_bf16 v[118:121], v[150:153], v[182:185], v[118:121]
	v_mfma_f32_16x16x32_bf16 v[114:117], v[158:161], v[182:185], v[114:117]
	v_mfma_f32_16x16x32_bf16 v[110:113], v[150:153], v[208:211], v[110:113]
	v_mfma_f32_16x16x32_bf16 v[102:105], v[158:161], v[208:211], v[102:105]
	v_mfma_f32_16x16x32_bf16 v[94:97], v[150:153], v[216:219], v[94:97]
	v_mfma_f32_16x16x32_bf16 v[86:89], v[158:161], v[216:219], v[86:89]
	v_mfma_f32_16x16x32_bf16 v[78:81], v[150:153], v[224:227], v[78:81]
	v_mfma_f32_16x16x32_bf16 v[70:73], v[158:161], v[224:227], v[70:73]
	v_mfma_f32_16x16x32_bf16 v[126:129], v[162:165], v[178:181], v[126:129]
	v_mfma_f32_16x16x32_bf16 v[122:125], v[170:173], v[178:181], v[122:125]
	v_mfma_f32_16x16x32_bf16 v[106:109], v[162:165], v[204:207], v[106:109]
	v_mfma_f32_16x16x32_bf16 v[98:101], v[170:173], v[204:207], v[98:101]
	v_mfma_f32_16x16x32_bf16 v[90:93], v[162:165], v[212:215], v[90:93]
	v_mfma_f32_16x16x32_bf16 v[82:85], v[170:173], v[212:215], v[82:85]
	v_mfma_f32_16x16x32_bf16 v[74:77], v[162:165], v[220:223], v[74:77]
	v_mfma_f32_16x16x32_bf16 v[66:69], v[170:173], v[220:223], v[66:69]
	v_mfma_f32_16x16x32_bf16 v[126:129], v[166:169], v[182:185], v[126:129]
	v_mfma_f32_16x16x32_bf16 v[122:125], v[174:177], v[182:185], v[122:125]
	v_mfma_f32_16x16x32_bf16 v[106:109], v[166:169], v[208:211], v[106:109]
	v_mfma_f32_16x16x32_bf16 v[98:101], v[174:177], v[208:211], v[98:101]
	v_mfma_f32_16x16x32_bf16 v[90:93], v[166:169], v[216:219], v[90:93]
	v_mfma_f32_16x16x32_bf16 v[82:85], v[174:177], v[216:219], v[82:85]
	v_mfma_f32_16x16x32_bf16 v[74:77], v[166:169], v[224:227], v[74:77]
	v_mfma_f32_16x16x32_bf16 v[66:69], v[174:177], v[224:227], v[66:69]
	s_barrier
	s_setprio 0
	s_add_i32 s63, s63, s4
	s_mov_b32 m0, s63
	ds_read_b128 v[178:181], v145 offset:16384
	ds_read_b128 v[182:185], v145 offset:17408
	ds_read_b128 v[204:207], v145 offset:18432
	ds_read_b128 v[208:211], v145 offset:19456
	ds_read_b128 v[212:215], v145 offset:20480
	ds_read_b128 v[216:219], v145 offset:21504
	ds_read_b128 v[220:223], v145 offset:22528
	ds_read_b128 v[224:227], v145 offset:23552
	global_load_lds_dwordx4 v134, s[48:49]
	s_add_i32 m0, s63, 0x2000
	s_add_u32 s64, s48, 0x40000
	s_addc_u32 s65, s49, 0
	s_add_i32 s63, s66, s4
	global_load_lds_dwordx4 v130, s[48:49]
	s_mov_b32 m0, s63
	s_nop 0
	global_load_lds_dwordx4 v134, s[64:65]
	s_add_i32 m0, s63, 0x2000
	s_nop 0
	global_load_lds_dwordx4 v130, s[64:65]
	s_mov_b32 m0, s5
	s_nop 0
	global_load_lds_dwordx4 v136, s[50:51]
	s_mov_b32 m0, s6
	s_nop 0
	global_load_lds_dwordx4 v132, s[50:51]
	s_waitcnt vmcnt(8)
	s_waitcnt lgkmcnt(0)
	s_setprio 1
	s_barrier
	v_mfma_f32_16x16x32_bf16 v[62:65], v[146:149], v[178:181], v[62:65]
	v_mfma_f32_16x16x32_bf16 v[54:57], v[154:157], v[178:181], v[54:57]
	v_mfma_f32_16x16x32_bf16 v[46:49], v[146:149], v[204:207], v[46:49]
	v_mfma_f32_16x16x32_bf16 v[38:41], v[154:157], v[204:207], v[38:41]
	v_mfma_f32_16x16x32_bf16 v[30:33], v[146:149], v[212:215], v[30:33]
	v_mfma_f32_16x16x32_bf16 v[22:25], v[154:157], v[212:215], v[22:25]
	v_mfma_f32_16x16x32_bf16 v[14:17], v[146:149], v[220:223], v[14:17]
	v_mfma_f32_16x16x32_bf16 v[6:9], v[154:157], v[220:223], v[6:9]
	v_mfma_f32_16x16x32_bf16 v[62:65], v[150:153], v[182:185], v[62:65]
	v_mfma_f32_16x16x32_bf16 v[54:57], v[158:161], v[182:185], v[54:57]
	v_mfma_f32_16x16x32_bf16 v[46:49], v[150:153], v[208:211], v[46:49]
	v_mfma_f32_16x16x32_bf16 v[38:41], v[158:161], v[208:211], v[38:41]
	v_mfma_f32_16x16x32_bf16 v[30:33], v[150:153], v[216:219], v[30:33]
	v_mfma_f32_16x16x32_bf16 v[22:25], v[158:161], v[216:219], v[22:25]
	v_mfma_f32_16x16x32_bf16 v[14:17], v[150:153], v[224:227], v[14:17]
	v_mfma_f32_16x16x32_bf16 v[6:9], v[158:161], v[224:227], v[6:9]
	v_mfma_f32_16x16x32_bf16 v[58:61], v[162:165], v[178:181], v[58:61]
	v_mfma_f32_16x16x32_bf16 v[50:53], v[170:173], v[178:181], v[50:53]
	v_mfma_f32_16x16x32_bf16 v[42:45], v[162:165], v[204:207], v[42:45]
	v_mfma_f32_16x16x32_bf16 v[34:37], v[170:173], v[204:207], v[34:37]
	v_mfma_f32_16x16x32_bf16 v[26:29], v[162:165], v[212:215], v[26:29]
	v_mfma_f32_16x16x32_bf16 v[18:21], v[170:173], v[212:215], v[18:21]
	v_mfma_f32_16x16x32_bf16 v[10:13], v[162:165], v[220:223], v[10:13]
	v_mfma_f32_16x16x32_bf16 v[2:5], v[170:173], v[220:223], v[2:5]
	v_mfma_f32_16x16x32_bf16 v[58:61], v[166:169], v[182:185], v[58:61]
	v_mfma_f32_16x16x32_bf16 v[50:53], v[174:177], v[182:185], v[50:53]
	v_mfma_f32_16x16x32_bf16 v[42:45], v[166:169], v[208:211], v[42:45]
	v_mfma_f32_16x16x32_bf16 v[34:37], v[174:177], v[208:211], v[34:37]
	v_mfma_f32_16x16x32_bf16 v[26:29], v[166:169], v[216:219], v[26:29]
	v_mfma_f32_16x16x32_bf16 v[18:21], v[174:177], v[216:219], v[18:21]
	v_mfma_f32_16x16x32_bf16 v[10:13], v[166:169], v[224:227], v[10:13]
	v_mfma_f32_16x16x32_bf16 v[2:5], v[174:177], v[224:227], v[2:5]
	s_barrier
	s_setprio 0
	s_add_i32 s63, 0, 0x18000
	v_add_u32_e32 v0, s63, v144
	s_add_i32 s64, 0, 0x1c000
	ds_read_b128 v[146:149], v0
	ds_read_b128 v[150:153], v0 offset:1024
	ds_read_b128 v[154:157], v0 offset:2048
	ds_read_b128 v[158:161], v0 offset:3072
	v_add_u32_e32 v0, s64, v144
	ds_read_b128 v[162:165], v0
	ds_read_b128 v[166:169], v0 offset:1024
	ds_read_b128 v[170:173], v0 offset:2048
	ds_read_b128 v[174:177], v0 offset:3072
	s_add_u32 s50, s50, 0x40000
	s_addc_u32 s51, s51, 0
	s_mov_b32 m0, s7
	ds_read_b128 v[178:181], v145 offset:32768
	ds_read_b128 v[182:185], v145 offset:33792
	ds_read_b128 v[204:207], v145 offset:34816
	ds_read_b128 v[208:211], v145 offset:35840
	ds_read_b128 v[212:215], v145 offset:36864
	ds_read_b128 v[216:219], v145 offset:37888
	ds_read_b128 v[220:223], v145 offset:38912
	ds_read_b128 v[224:227], v145 offset:39936
	global_load_lds_dwordx4 v136, s[50:51]
	s_mov_b32 m0, s52
	s_nop 0
	global_load_lds_dwordx4 v132, s[50:51]
	s_waitcnt vmcnt(8)
	s_waitcnt lgkmcnt(0)
	s_setprio 1
	s_barrier
	v_mfma_f32_16x16x32_bf16 v[118:121], v[146:149], v[178:181], v[118:121]
	v_mfma_f32_16x16x32_bf16 v[114:117], v[154:157], v[178:181], v[114:117]
	v_mfma_f32_16x16x32_bf16 v[110:113], v[146:149], v[204:207], v[110:113]
	v_mfma_f32_16x16x32_bf16 v[102:105], v[154:157], v[204:207], v[102:105]
	v_mfma_f32_16x16x32_bf16 v[94:97], v[146:149], v[212:215], v[94:97]
	v_mfma_f32_16x16x32_bf16 v[86:89], v[154:157], v[212:215], v[86:89]
	v_mfma_f32_16x16x32_bf16 v[78:81], v[146:149], v[220:223], v[78:81]
	v_mfma_f32_16x16x32_bf16 v[70:73], v[154:157], v[220:223], v[70:73]
	v_mfma_f32_16x16x32_bf16 v[118:121], v[150:153], v[182:185], v[118:121]
	v_mfma_f32_16x16x32_bf16 v[114:117], v[158:161], v[182:185], v[114:117]
	v_mfma_f32_16x16x32_bf16 v[110:113], v[150:153], v[208:211], v[110:113]
	v_mfma_f32_16x16x32_bf16 v[102:105], v[158:161], v[208:211], v[102:105]
	v_mfma_f32_16x16x32_bf16 v[94:97], v[150:153], v[216:219], v[94:97]
	v_mfma_f32_16x16x32_bf16 v[86:89], v[158:161], v[216:219], v[86:89]
	v_mfma_f32_16x16x32_bf16 v[78:81], v[150:153], v[224:227], v[78:81]
	v_mfma_f32_16x16x32_bf16 v[70:73], v[158:161], v[224:227], v[70:73]
	v_mfma_f32_16x16x32_bf16 v[126:129], v[162:165], v[178:181], v[126:129]
	v_mfma_f32_16x16x32_bf16 v[122:125], v[170:173], v[178:181], v[122:125]
	v_mfma_f32_16x16x32_bf16 v[106:109], v[162:165], v[204:207], v[106:109]
	v_mfma_f32_16x16x32_bf16 v[98:101], v[170:173], v[204:207], v[98:101]
	v_mfma_f32_16x16x32_bf16 v[90:93], v[162:165], v[212:215], v[90:93]
	v_mfma_f32_16x16x32_bf16 v[82:85], v[170:173], v[212:215], v[82:85]
	v_mfma_f32_16x16x32_bf16 v[74:77], v[162:165], v[220:223], v[74:77]
	v_mfma_f32_16x16x32_bf16 v[66:69], v[170:173], v[220:223], v[66:69]
	v_mfma_f32_16x16x32_bf16 v[126:129], v[166:169], v[182:185], v[126:129]
	v_mfma_f32_16x16x32_bf16 v[122:125], v[174:177], v[182:185], v[122:125]
	v_mfma_f32_16x16x32_bf16 v[106:109], v[166:169], v[208:211], v[106:109]
	v_mfma_f32_16x16x32_bf16 v[98:101], v[174:177], v[208:211], v[98:101]
	v_mfma_f32_16x16x32_bf16 v[90:93], v[166:169], v[216:219], v[90:93]
	v_mfma_f32_16x16x32_bf16 v[82:85], v[174:177], v[216:219], v[82:85]
	v_mfma_f32_16x16x32_bf16 v[74:77], v[166:169], v[224:227], v[74:77]
	v_mfma_f32_16x16x32_bf16 v[66:69], v[174:177], v[224:227], v[66:69]
	s_barrier
	s_setprio 0
	s_add_i32 s65, s63, s4
	s_add_u32 s48, s48, 0x80
	s_addc_u32 s49, s49, 0
	s_mov_b32 m0, s65
	ds_read_b128 v[178:181], v145 offset:49152
	ds_read_b128 v[182:185], v145 offset:50176
	ds_read_b128 v[204:207], v145 offset:51200
	ds_read_b128 v[208:211], v145 offset:52224
	ds_read_b128 v[212:215], v145 offset:53248
	ds_read_b128 v[216:219], v145 offset:54272
	ds_read_b128 v[220:223], v145 offset:55296
	ds_read_b128 v[224:227], v145 offset:56320
	global_load_lds_dwordx4 v134, s[48:49]
	s_add_i32 m0, s65, 0x2000
	s_add_i32 s65, s64, s4
	global_load_lds_dwordx4 v130, s[48:49]
	s_add_u32 s48, s48, 0x40000
	s_addc_u32 s49, s49, 0
	s_mov_b32 m0, s65
	s_sub_u32 s50, s50, 0x3ff80
	global_load_lds_dwordx4 v134, s[48:49]
	s_subb_u32 s51, s51, 0
	s_add_i32 m0, s65, 0x2000
	s_nop 0
	global_load_lds_dwordx4 v130, s[48:49]
	s_mov_b32 m0, s55
	s_nop 0
	global_load_lds_dwordx4 v136, s[50:51]
	s_mov_b32 m0, s56
	s_nop 0
	global_load_lds_dwordx4 v132, s[50:51]
	s_waitcnt vmcnt(8)
	s_waitcnt lgkmcnt(0)
	s_setprio 1
	s_barrier
	v_mfma_f32_16x16x32_bf16 v[62:65], v[146:149], v[178:181], v[62:65]
	v_mfma_f32_16x16x32_bf16 v[54:57], v[154:157], v[178:181], v[54:57]
	v_mfma_f32_16x16x32_bf16 v[46:49], v[146:149], v[204:207], v[46:49]
	v_mfma_f32_16x16x32_bf16 v[38:41], v[154:157], v[204:207], v[38:41]
	v_mfma_f32_16x16x32_bf16 v[30:33], v[146:149], v[212:215], v[30:33]
	v_mfma_f32_16x16x32_bf16 v[22:25], v[154:157], v[212:215], v[22:25]
	v_mfma_f32_16x16x32_bf16 v[14:17], v[146:149], v[220:223], v[14:17]
	v_mfma_f32_16x16x32_bf16 v[6:9], v[154:157], v[220:223], v[6:9]
	v_mfma_f32_16x16x32_bf16 v[62:65], v[150:153], v[182:185], v[62:65]
	v_mfma_f32_16x16x32_bf16 v[54:57], v[158:161], v[182:185], v[54:57]
	v_mfma_f32_16x16x32_bf16 v[46:49], v[150:153], v[208:211], v[46:49]
	v_mfma_f32_16x16x32_bf16 v[38:41], v[158:161], v[208:211], v[38:41]
	v_mfma_f32_16x16x32_bf16 v[30:33], v[150:153], v[216:219], v[30:33]
	v_mfma_f32_16x16x32_bf16 v[22:25], v[158:161], v[216:219], v[22:25]
	v_mfma_f32_16x16x32_bf16 v[14:17], v[150:153], v[224:227], v[14:17]
	v_mfma_f32_16x16x32_bf16 v[6:9], v[158:161], v[224:227], v[6:9]
	v_mfma_f32_16x16x32_bf16 v[58:61], v[162:165], v[178:181], v[58:61]
	v_mfma_f32_16x16x32_bf16 v[50:53], v[170:173], v[178:181], v[50:53]
	v_mfma_f32_16x16x32_bf16 v[42:45], v[162:165], v[204:207], v[42:45]
	v_mfma_f32_16x16x32_bf16 v[34:37], v[170:173], v[204:207], v[34:37]
	v_mfma_f32_16x16x32_bf16 v[26:29], v[162:165], v[212:215], v[26:29]
	v_mfma_f32_16x16x32_bf16 v[18:21], v[170:173], v[212:215], v[18:21]
	v_mfma_f32_16x16x32_bf16 v[10:13], v[162:165], v[220:223], v[10:13]
	v_mfma_f32_16x16x32_bf16 v[2:5], v[170:173], v[220:223], v[2:5]
	v_mfma_f32_16x16x32_bf16 v[58:61], v[166:169], v[182:185], v[58:61]
	v_mfma_f32_16x16x32_bf16 v[50:53], v[174:177], v[182:185], v[50:53]
	v_mfma_f32_16x16x32_bf16 v[42:45], v[166:169], v[208:211], v[42:45]
	v_mfma_f32_16x16x32_bf16 v[34:37], v[174:177], v[208:211], v[34:37]
	v_mfma_f32_16x16x32_bf16 v[26:29], v[166:169], v[216:219], v[26:29]
	v_mfma_f32_16x16x32_bf16 v[18:21], v[174:177], v[216:219], v[18:21]
	v_mfma_f32_16x16x32_bf16 v[10:13], v[166:169], v[224:227], v[10:13]
	v_mfma_f32_16x16x32_bf16 v[2:5], v[174:177], v[224:227], v[2:5]
	s_barrier
	s_setprio 0
	s_add_i32 s62, s62, 2
	s_add_u32 s46, s46, 0x100
	s_addc_u32 s47, s47, 0
	s_add_u32 s60, s60, 0x100
	s_addc_u32 s61, s61, 0
	s_cmp_gt_u32 s62, 13
	s_cbranch_scc0 .LBB0_229
	s_and_b64 vcc, exec, s[20:21]
	s_cbranch_vccz .LBB0_232
	s_barrier

.Lrb2_skip:
	s_add_u32 s54, s52, 0xfffc0080
	s_addc_u32 s55, s53, -1
	s_add_i32 s67, 0, 0x10000
	s_cmp_eq_u32 s66, 12
	s_cselect_b32 s57, s19, s55
	s_cselect_b32 s56, s45, s54
	v_add_u32_e32 v0, s67, v158
	s_cselect_b32 s55, s41, s65
	s_cselect_b32 s54, s51, s64
	s_add_i32 s70, 0, 0x14000
	ds_read_b128 v[142:145], v0
	ds_read_b128 v[146:149], v0 offset:1024
	ds_read_b128 v[150:153], v0 offset:2048
	ds_read_b128 v[160:163], v0 offset:3072
	v_add_u32_e32 v0, s70, v158
	ds_read_b128 v[164:167], v0
	ds_read_b128 v[168:171], v0 offset:1024
	ds_read_b128 v[172:175], v0 offset:2048
	ds_read_b128 v[176:179], v0 offset:3072
	s_add_i32 m0, s59, 0xc000
	ds_read_b128 v[180:183], v159
	ds_read_b128 v[204:207], v159 offset:1024
	ds_read_b128 v[208:211], v159 offset:2048
	ds_read_b128 v[212:215], v159 offset:3072
	ds_read_b128 v[216:219], v159 offset:4096
	ds_read_b128 v[220:223], v159 offset:5120
	ds_read_b128 v[224:227], v159 offset:6144
	ds_read_b128 v[228:231], v159 offset:7168
	global_load_lds_dwordx4 v138, s[52:53]
	s_add_i32 m0, s59, 0xe000
	s_nop 0
	global_load_lds_dwordx4 v140, s[52:53]
	s_waitcnt vmcnt(8)
	s_waitcnt lgkmcnt(0)
	s_setprio 1
	s_barrier
	v_mfma_f32_16x16x32_bf16 v[126:129], v[142:145], v[180:183], 0
	v_mfma_f32_16x16x32_bf16 v[122:125], v[150:153], v[180:183], 0
	v_mfma_f32_16x16x32_bf16 v[110:113], v[142:145], v[208:211], 0
	v_mfma_f32_16x16x32_bf16 v[106:109], v[150:153], v[208:211], 0
	v_mfma_f32_16x16x32_bf16 v[94:97], v[142:145], v[216:219], 0
	v_mfma_f32_16x16x32_bf16 v[90:93], v[150:153], v[216:219], 0
	v_mfma_f32_16x16x32_bf16 v[78:81], v[142:145], v[224:227], 0
	v_mfma_f32_16x16x32_bf16 v[74:77], v[150:153], v[224:227], 0
	v_mfma_f32_16x16x32_bf16 v[126:129], v[146:149], v[204:207], v[126:129]
	v_mfma_f32_16x16x32_bf16 v[122:125], v[160:163], v[204:207], v[122:125]
	v_mfma_f32_16x16x32_bf16 v[110:113], v[146:149], v[212:215], v[110:113]
	v_mfma_f32_16x16x32_bf16 v[106:109], v[160:163], v[212:215], v[106:109]
	v_mfma_f32_16x16x32_bf16 v[94:97], v[146:149], v[220:223], v[94:97]
	v_mfma_f32_16x16x32_bf16 v[90:93], v[160:163], v[220:223], v[90:93]
	v_mfma_f32_16x16x32_bf16 v[78:81], v[146:149], v[228:231], v[78:81]
	v_mfma_f32_16x16x32_bf16 v[74:77], v[160:163], v[228:231], v[74:77]
	v_mfma_f32_16x16x32_bf16 v[118:121], v[164:167], v[180:183], 0
	v_mfma_f32_16x16x32_bf16 v[114:117], v[172:175], v[180:183], 0
	v_mfma_f32_16x16x32_bf16 v[102:105], v[164:167], v[208:211], 0
	v_mfma_f32_16x16x32_bf16 v[98:101], v[172:175], v[208:211], 0
	v_mfma_f32_16x16x32_bf16 v[86:89], v[164:167], v[216:219], 0
	v_mfma_f32_16x16x32_bf16 v[82:85], v[172:175], v[216:219], 0
	v_mfma_f32_16x16x32_bf16 v[70:73], v[164:167], v[224:227], 0
	v_mfma_f32_16x16x32_bf16 v[66:69], v[172:175], v[224:227], 0
	v_mfma_f32_16x16x32_bf16 v[118:121], v[168:171], v[204:207], v[118:121]
	v_mfma_f32_16x16x32_bf16 v[114:117], v[176:179], v[204:207], v[114:117]
	v_mfma_f32_16x16x32_bf16 v[102:105], v[168:171], v[212:215], v[102:105]
	v_mfma_f32_16x16x32_bf16 v[98:101], v[176:179], v[212:215], v[98:101]
	v_mfma_f32_16x16x32_bf16 v[86:89], v[168:171], v[220:223], v[86:89]
	v_mfma_f32_16x16x32_bf16 v[82:85], v[176:179], v[220:223], v[82:85]
	v_mfma_f32_16x16x32_bf16 v[70:73], v[168:171], v[228:231], v[70:73]
	v_mfma_f32_16x16x32_bf16 v[66:69], v[176:179], v[228:231], v[66:69]
	s_barrier
	s_setprio 0
	s_add_i32 s67, s67, s58
	s_mov_b32 m0, s67
	ds_read_b128 v[180:183], v159 offset:16384
	ds_read_b128 v[204:207], v159 offset:17408
	ds_read_b128 v[208:211], v159 offset:18432
	ds_read_b128 v[212:215], v159 offset:19456
	ds_read_b128 v[216:219], v159 offset:20480
	ds_read_b128 v[220:223], v159 offset:21504
	ds_read_b128 v[224:227], v159 offset:22528
	ds_read_b128 v[228:231], v159 offset:23552
	global_load_lds_dwordx4 v134, s[54:55]
	s_add_i32 m0, s67, 0x2000
	s_add_u32 s68, s54, 0x40000
	s_addc_u32 s69, s55, 0
	s_add_i32 s67, s70, s58
	global_load_lds_dwordx4 v130, s[54:55]
	s_mov_b32 m0, s67
	s_nop 0
	global_load_lds_dwordx4 v134, s[68:69]
	s_add_i32 m0, s67, 0x2000
	s_nop 0
	global_load_lds_dwordx4 v130, s[68:69]
	s_mov_b32 m0, s59
	s_nop 0
	global_load_lds_dwordx4 v136, s[56:57]
	s_mov_b32 m0, s60
	s_nop 0
	global_load_lds_dwordx4 v132, s[56:57]
	s_waitcnt vmcnt(8)
	s_waitcnt lgkmcnt(0)
	s_setprio 1
	s_barrier
	v_mfma_f32_16x16x32_bf16 v[62:65], v[142:145], v[180:183], 0
	v_mfma_f32_16x16x32_bf16 v[58:61], v[150:153], v[180:183], 0
	v_mfma_f32_16x16x32_bf16 v[46:49], v[142:145], v[208:211], 0
	v_mfma_f32_16x16x32_bf16 v[42:45], v[150:153], v[208:211], 0
	v_mfma_f32_16x16x32_bf16 v[30:33], v[142:145], v[216:219], 0
	v_mfma_f32_16x16x32_bf16 v[26:29], v[150:153], v[216:219], 0
	v_mfma_f32_16x16x32_bf16 v[14:17], v[142:145], v[224:227], 0
	v_mfma_f32_16x16x32_bf16 v[10:13], v[150:153], v[224:227], 0
	v_mfma_f32_16x16x32_bf16 v[62:65], v[146:149], v[204:207], v[62:65]
	v_mfma_f32_16x16x32_bf16 v[58:61], v[160:163], v[204:207], v[58:61]
	v_mfma_f32_16x16x32_bf16 v[46:49], v[146:149], v[212:215], v[46:49]
	v_mfma_f32_16x16x32_bf16 v[42:45], v[160:163], v[212:215], v[42:45]
	v_mfma_f32_16x16x32_bf16 v[30:33], v[146:149], v[220:223], v[30:33]
	v_mfma_f32_16x16x32_bf16 v[26:29], v[160:163], v[220:223], v[26:29]
	v_mfma_f32_16x16x32_bf16 v[14:17], v[146:149], v[228:231], v[14:17]
	v_mfma_f32_16x16x32_bf16 v[10:13], v[160:163], v[228:231], v[10:13]
	v_mfma_f32_16x16x32_bf16 v[54:57], v[164:167], v[180:183], 0
	v_mfma_f32_16x16x32_bf16 v[50:53], v[172:175], v[180:183], 0
	v_mfma_f32_16x16x32_bf16 v[38:41], v[164:167], v[208:211], 0
	v_mfma_f32_16x16x32_bf16 v[34:37], v[172:175], v[208:211], 0
	v_mfma_f32_16x16x32_bf16 v[22:25], v[164:167], v[216:219], 0
	v_mfma_f32_16x16x32_bf16 v[18:21], v[172:175], v[216:219], 0
	v_mfma_f32_16x16x32_bf16 v[6:9], v[164:167], v[224:227], 0
	v_mfma_f32_16x16x32_bf16 v[2:5], v[172:175], v[224:227], 0
	v_mfma_f32_16x16x32_bf16 v[54:57], v[168:171], v[204:207], v[54:57]
	v_mfma_f32_16x16x32_bf16 v[50:53], v[176:179], v[204:207], v[50:53]
	v_mfma_f32_16x16x32_bf16 v[38:41], v[168:171], v[212:215], v[38:41]
	v_mfma_f32_16x16x32_bf16 v[34:37], v[176:179], v[212:215], v[34:37]
	v_mfma_f32_16x16x32_bf16 v[22:25], v[168:171], v[220:223], v[22:25]
	v_mfma_f32_16x16x32_bf16 v[18:21], v[176:179], v[220:223], v[18:21]
	v_mfma_f32_16x16x32_bf16 v[6:9], v[168:171], v[228:231], v[6:9]
	v_mfma_f32_16x16x32_bf16 v[2:5], v[176:179], v[228:231], v[2:5]
	s_barrier
	s_setprio 0
	s_add_i32 s67, 0, 0x18000
	v_add_u32_e32 v0, s67, v158
	s_add_i32 s68, 0, 0x1c000
	ds_read_b128 v[142:145], v0
	ds_read_b128 v[146:149], v0 offset:1024
	ds_read_b128 v[150:153], v0 offset:2048
	ds_read_b128 v[160:163], v0 offset:3072
	v_add_u32_e32 v0, s68, v158
	ds_read_b128 v[164:167], v0
	ds_read_b128 v[168:171], v0 offset:1024
	ds_read_b128 v[172:175], v0 offset:2048
	ds_read_b128 v[176:179], v0 offset:3072
	s_add_u32 s56, s56, 0x40000
	s_addc_u32 s57, s57, 0
	s_mov_b32 m0, s61
	ds_read_b128 v[180:183], v159 offset:32768
	ds_read_b128 v[204:207], v159 offset:33792
	ds_read_b128 v[208:211], v159 offset:34816
	ds_read_b128 v[212:215], v159 offset:35840
	ds_read_b128 v[216:219], v159 offset:36864
	ds_read_b128 v[220:223], v159 offset:37888
	ds_read_b128 v[224:227], v159 offset:38912
	ds_read_b128 v[228:231], v159 offset:39936
	global_load_lds_dwordx4 v136, s[56:57]
	s_mov_b32 m0, s62
	s_nop 0
	global_load_lds_dwordx4 v132, s[56:57]
	s_waitcnt vmcnt(8)
	s_waitcnt lgkmcnt(0)
	s_setprio 1
	s_barrier
	v_mfma_f32_16x16x32_bf16 v[126:129], v[142:145], v[180:183], v[126:129]
	v_mfma_f32_16x16x32_bf16 v[122:125], v[150:153], v[180:183], v[122:125]
	v_mfma_f32_16x16x32_bf16 v[110:113], v[142:145], v[208:211], v[110:113]
	v_mfma_f32_16x16x32_bf16 v[106:109], v[150:153], v[208:211], v[106:109]
	v_mfma_f32_16x16x32_bf16 v[94:97], v[142:145], v[216:219], v[94:97]
	v_mfma_f32_16x16x32_bf16 v[90:93], v[150:153], v[216:219], v[90:93]
	v_mfma_f32_16x16x32_bf16 v[78:81], v[142:145], v[224:227], v[78:81]
	v_mfma_f32_16x16x32_bf16 v[74:77], v[150:153], v[224:227], v[74:77]
	v_mfma_f32_16x16x32_bf16 v[126:129], v[146:149], v[204:207], v[126:129]
	v_mfma_f32_16x16x32_bf16 v[122:125], v[160:163], v[204:207], v[122:125]
	v_mfma_f32_16x16x32_bf16 v[110:113], v[146:149], v[212:215], v[110:113]
	v_mfma_f32_16x16x32_bf16 v[106:109], v[160:163], v[212:215], v[106:109]
	v_mfma_f32_16x16x32_bf16 v[94:97], v[146:149], v[220:223], v[94:97]
	v_mfma_f32_16x16x32_bf16 v[90:93], v[160:163], v[220:223], v[90:93]
	v_mfma_f32_16x16x32_bf16 v[78:81], v[146:149], v[228:231], v[78:81]
	v_mfma_f32_16x16x32_bf16 v[74:77], v[160:163], v[228:231], v[74:77]
	v_mfma_f32_16x16x32_bf16 v[118:121], v[164:167], v[180:183], v[118:121]
	v_mfma_f32_16x16x32_bf16 v[114:117], v[172:175], v[180:183], v[114:117]
	v_mfma_f32_16x16x32_bf16 v[102:105], v[164:167], v[208:211], v[102:105]
	v_mfma_f32_16x16x32_bf16 v[98:101], v[172:175], v[208:211], v[98:101]
	v_mfma_f32_16x16x32_bf16 v[86:89], v[164:167], v[216:219], v[86:89]
	v_mfma_f32_16x16x32_bf16 v[82:85], v[172:175], v[216:219], v[82:85]
	v_mfma_f32_16x16x32_bf16 v[70:73], v[164:167], v[224:227], v[70:73]
	v_mfma_f32_16x16x32_bf16 v[66:69], v[172:175], v[224:227], v[66:69]
	v_mfma_f32_16x16x32_bf16 v[118:121], v[168:171], v[204:207], v[118:121]
	v_mfma_f32_16x16x32_bf16 v[114:117], v[176:179], v[204:207], v[114:117]
	v_mfma_f32_16x16x32_bf16 v[102:105], v[168:171], v[212:215], v[102:105]
	v_mfma_f32_16x16x32_bf16 v[98:101], v[176:179], v[212:215], v[98:101]
	v_mfma_f32_16x16x32_bf16 v[86:89], v[168:171], v[220:223], v[86:89]
	v_mfma_f32_16x16x32_bf16 v[82:85], v[176:179], v[220:223], v[82:85]
	v_mfma_f32_16x16x32_bf16 v[70:73], v[168:171], v[228:231], v[70:73]
	v_mfma_f32_16x16x32_bf16 v[66:69], v[176:179], v[228:231], v[66:69]
	s_barrier
	s_setprio 0
	s_add_i32 s69, s67, s58
	s_add_u32 s54, s54, 0x80
	s_addc_u32 s55, s55, 0
	s_mov_b32 m0, s69
	ds_read_b128 v[180:183], v159 offset:49152
	ds_read_b128 v[204:207], v159 offset:50176
	ds_read_b128 v[208:211], v159 offset:51200
	ds_read_b128 v[212:215], v159 offset:52224
	ds_read_b128 v[216:219], v159 offset:53248
	ds_read_b128 v[220:223], v159 offset:54272
	ds_read_b128 v[224:227], v159 offset:55296
	ds_read_b128 v[228:231], v159 offset:56320
	global_load_lds_dwordx4 v134, s[54:55]
	s_add_i32 m0, s69, 0x2000
	s_add_i32 s69, s68, s58
	global_load_lds_dwordx4 v130, s[54:55]
	s_add_u32 s54, s54, 0x40000
	s_addc_u32 s55, s55, 0
	s_mov_b32 m0, s69
	s_sub_u32 s56, s56, 0x3ff80
	global_load_lds_dwordx4 v134, s[54:55]
	s_subb_u32 s57, s57, 0
	s_add_i32 m0, s69, 0x2000
	s_nop 0
	global_load_lds_dwordx4 v130, s[54:55]
	s_mov_b32 m0, s5
	s_nop 0
	global_load_lds_dwordx4 v136, s[56:57]
	s_mov_b32 m0, s6
	s_nop 0
	global_load_lds_dwordx4 v132, s[56:57]
	s_waitcnt vmcnt(8)
	s_waitcnt lgkmcnt(0)
	s_setprio 1
	s_barrier
	v_mfma_f32_16x16x32_bf16 v[62:65], v[142:145], v[180:183], v[62:65]
	v_mfma_f32_16x16x32_bf16 v[58:61], v[150:153], v[180:183], v[58:61]
	v_mfma_f32_16x16x32_bf16 v[46:49], v[142:145], v[208:211], v[46:49]
	v_mfma_f32_16x16x32_bf16 v[42:45], v[150:153], v[208:211], v[42:45]
	v_mfma_f32_16x16x32_bf16 v[30:33], v[142:145], v[216:219], v[30:33]
	v_mfma_f32_16x16x32_bf16 v[26:29], v[150:153], v[216:219], v[26:29]
	v_mfma_f32_16x16x32_bf16 v[14:17], v[142:145], v[224:227], v[14:17]
	v_mfma_f32_16x16x32_bf16 v[10:13], v[150:153], v[224:227], v[10:13]
	v_mfma_f32_16x16x32_bf16 v[62:65], v[146:149], v[204:207], v[62:65]
	v_mfma_f32_16x16x32_bf16 v[58:61], v[160:163], v[204:207], v[58:61]
	v_mfma_f32_16x16x32_bf16 v[46:49], v[146:149], v[212:215], v[46:49]
	v_mfma_f32_16x16x32_bf16 v[42:45], v[160:163], v[212:215], v[42:45]
	v_mfma_f32_16x16x32_bf16 v[30:33], v[146:149], v[220:223], v[30:33]
	v_mfma_f32_16x16x32_bf16 v[26:29], v[160:163], v[220:223], v[26:29]
	v_mfma_f32_16x16x32_bf16 v[14:17], v[146:149], v[228:231], v[14:17]
	v_mfma_f32_16x16x32_bf16 v[10:13], v[160:163], v[228:231], v[10:13]
	v_mfma_f32_16x16x32_bf16 v[54:57], v[164:167], v[180:183], v[54:57]
	v_mfma_f32_16x16x32_bf16 v[50:53], v[172:175], v[180:183], v[50:53]
	v_mfma_f32_16x16x32_bf16 v[38:41], v[164:167], v[208:211], v[38:41]
	v_mfma_f32_16x16x32_bf16 v[34:37], v[172:175], v[208:211], v[34:37]
	v_mfma_f32_16x16x32_bf16 v[22:25], v[164:167], v[216:219], v[22:25]
	v_mfma_f32_16x16x32_bf16 v[18:21], v[172:175], v[216:219], v[18:21]
	v_mfma_f32_16x16x32_bf16 v[6:9], v[164:167], v[224:227], v[6:9]
	v_mfma_f32_16x16x32_bf16 v[2:5], v[172:175], v[224:227], v[2:5]
	v_mfma_f32_16x16x32_bf16 v[54:57], v[168:171], v[204:207], v[54:57]
	v_mfma_f32_16x16x32_bf16 v[50:53], v[176:179], v[204:207], v[50:53]
	v_mfma_f32_16x16x32_bf16 v[38:41], v[168:171], v[212:215], v[38:41]
	v_mfma_f32_16x16x32_bf16 v[34:37], v[176:179], v[212:215], v[34:37]
	v_mfma_f32_16x16x32_bf16 v[22:25], v[168:171], v[220:223], v[22:25]
	v_mfma_f32_16x16x32_bf16 v[18:21], v[176:179], v[220:223], v[18:21]
	v_mfma_f32_16x16x32_bf16 v[6:9], v[168:171], v[228:231], v[6:9]
	v_mfma_f32_16x16x32_bf16 v[2:5], v[176:179], v[228:231], v[2:5]
	s_barrier
	s_setprio 0
	s_add_i32 s66, s66, 2
	s_add_u32 s52, s52, 0x100
	s_addc_u32 s53, s53, 0
	s_add_u32 s64, s64, 0x100
	s_addc_u32 s65, s65, 0
	s_cmp_gt_u32 s66, 13
.LBB0_422:
	s_add_u32 s54, s52, 0xfffc0080
	s_addc_u32 s55, s53, -1
	s_add_i32 s67, 0, 0x10000
	s_cmp_eq_u32 s66, 12
	s_cselect_b32 s57, s19, s55
	s_cselect_b32 s56, s45, s54
	v_add_u32_e32 v0, s67, v158
	s_cselect_b32 s55, s41, s65
	s_cselect_b32 s54, s51, s64
	s_add_i32 s70, 0, 0x14000
	ds_read_b128 v[142:145], v0
	ds_read_b128 v[146:149], v0 offset:1024
	ds_read_b128 v[150:153], v0 offset:2048
	ds_read_b128 v[160:163], v0 offset:3072
	v_add_u32_e32 v0, s70, v158
	ds_read_b128 v[164:167], v0
	ds_read_b128 v[168:171], v0 offset:1024
	ds_read_b128 v[172:175], v0 offset:2048
	ds_read_b128 v[176:179], v0 offset:3072
	s_add_i32 m0, s59, 0xc000
	ds_read_b128 v[180:183], v159
	ds_read_b128 v[204:207], v159 offset:1024
	ds_read_b128 v[208:211], v159 offset:2048
	ds_read_b128 v[212:215], v159 offset:3072
	ds_read_b128 v[216:219], v159 offset:4096
	ds_read_b128 v[220:223], v159 offset:5120
	ds_read_b128 v[224:227], v159 offset:6144
	ds_read_b128 v[228:231], v159 offset:7168
	global_load_lds_dwordx4 v138, s[52:53]
	s_add_i32 m0, s59, 0xe000
	s_nop 0
	global_load_lds_dwordx4 v140, s[52:53]
	s_waitcnt vmcnt(8)
	s_waitcnt lgkmcnt(0)
	s_setprio 1
	s_barrier
	v_mfma_f32_16x16x32_bf16 v[126:129], v[142:145], v[180:183], v[126:129]
	v_mfma_f32_16x16x32_bf16 v[122:125], v[150:153], v[180:183], v[122:125]
	v_mfma_f32_16x16x32_bf16 v[110:113], v[142:145], v[208:211], v[110:113]
	v_mfma_f32_16x16x32_bf16 v[106:109], v[150:153], v[208:211], v[106:109]
	v_mfma_f32_16x16x32_bf16 v[94:97], v[142:145], v[216:219], v[94:97]
	v_mfma_f32_16x16x32_bf16 v[90:93], v[150:153], v[216:219], v[90:93]
	v_mfma_f32_16x16x32_bf16 v[78:81], v[142:145], v[224:227], v[78:81]
	v_mfma_f32_16x16x32_bf16 v[74:77], v[150:153], v[224:227], v[74:77]
	v_mfma_f32_16x16x32_bf16 v[126:129], v[146:149], v[204:207], v[126:129]
	v_mfma_f32_16x16x32_bf16 v[122:125], v[160:163], v[204:207], v[122:125]
	v_mfma_f32_16x16x32_bf16 v[110:113], v[146:149], v[212:215], v[110:113]
	v_mfma_f32_16x16x32_bf16 v[106:109], v[160:163], v[212:215], v[106:109]
	v_mfma_f32_16x16x32_bf16 v[94:97], v[146:149], v[220:223], v[94:97]
	v_mfma_f32_16x16x32_bf16 v[90:93], v[160:163], v[220:223], v[90:93]
	v_mfma_f32_16x16x32_bf16 v[78:81], v[146:149], v[228:231], v[78:81]
	v_mfma_f32_16x16x32_bf16 v[74:77], v[160:163], v[228:231], v[74:77]
	v_mfma_f32_16x16x32_bf16 v[118:121], v[164:167], v[180:183], v[118:121]
	v_mfma_f32_16x16x32_bf16 v[114:117], v[172:175], v[180:183], v[114:117]
	v_mfma_f32_16x16x32_bf16 v[102:105], v[164:167], v[208:211], v[102:105]
	v_mfma_f32_16x16x32_bf16 v[98:101], v[172:175], v[208:211], v[98:101]
	v_mfma_f32_16x16x32_bf16 v[86:89], v[164:167], v[216:219], v[86:89]
	v_mfma_f32_16x16x32_bf16 v[82:85], v[172:175], v[216:219], v[82:85]
	v_mfma_f32_16x16x32_bf16 v[70:73], v[164:167], v[224:227], v[70:73]
	v_mfma_f32_16x16x32_bf16 v[66:69], v[172:175], v[224:227], v[66:69]
	v_mfma_f32_16x16x32_bf16 v[118:121], v[168:171], v[204:207], v[118:121]
	v_mfma_f32_16x16x32_bf16 v[114:117], v[176:179], v[204:207], v[114:117]
	v_mfma_f32_16x16x32_bf16 v[102:105], v[168:171], v[212:215], v[102:105]
	v_mfma_f32_16x16x32_bf16 v[98:101], v[176:179], v[212:215], v[98:101]
	v_mfma_f32_16x16x32_bf16 v[86:89], v[168:171], v[220:223], v[86:89]
	v_mfma_f32_16x16x32_bf16 v[82:85], v[176:179], v[220:223], v[82:85]
	v_mfma_f32_16x16x32_bf16 v[70:73], v[168:171], v[228:231], v[70:73]
	v_mfma_f32_16x16x32_bf16 v[66:69], v[176:179], v[228:231], v[66:69]
	s_barrier
	s_setprio 0
	s_add_i32 s67, s67, s58
	s_mov_b32 m0, s67
	ds_read_b128 v[180:183], v159 offset:16384
	ds_read_b128 v[204:207], v159 offset:17408
	ds_read_b128 v[208:211], v159 offset:18432
	ds_read_b128 v[212:215], v159 offset:19456
	ds_read_b128 v[216:219], v159 offset:20480
	ds_read_b128 v[220:223], v159 offset:21504
	ds_read_b128 v[224:227], v159 offset:22528
	ds_read_b128 v[228:231], v159 offset:23552
	global_load_lds_dwordx4 v134, s[54:55]
	s_add_i32 m0, s67, 0x2000
	s_add_u32 s68, s54, 0x40000
	s_addc_u32 s69, s55, 0
	s_add_i32 s67, s70, s58
	global_load_lds_dwordx4 v130, s[54:55]
	s_mov_b32 m0, s67
	s_nop 0
	global_load_lds_dwordx4 v134, s[68:69]
	s_add_i32 m0, s67, 0x2000
	s_nop 0
	global_load_lds_dwordx4 v130, s[68:69]
	s_mov_b32 m0, s59
	s_nop 0
	global_load_lds_dwordx4 v136, s[56:57]
	s_mov_b32 m0, s60
	s_nop 0
	global_load_lds_dwordx4 v132, s[56:57]
	s_waitcnt vmcnt(8)
	s_waitcnt lgkmcnt(0)
	s_setprio 1
	s_barrier
	v_mfma_f32_16x16x32_bf16 v[62:65], v[142:145], v[180:183], v[62:65]
	v_mfma_f32_16x16x32_bf16 v[58:61], v[150:153], v[180:183], v[58:61]
	v_mfma_f32_16x16x32_bf16 v[46:49], v[142:145], v[208:211], v[46:49]
	v_mfma_f32_16x16x32_bf16 v[42:45], v[150:153], v[208:211], v[42:45]
	v_mfma_f32_16x16x32_bf16 v[30:33], v[142:145], v[216:219], v[30:33]
	v_mfma_f32_16x16x32_bf16 v[26:29], v[150:153], v[216:219], v[26:29]
	v_mfma_f32_16x16x32_bf16 v[14:17], v[142:145], v[224:227], v[14:17]
	v_mfma_f32_16x16x32_bf16 v[10:13], v[150:153], v[224:227], v[10:13]
	v_mfma_f32_16x16x32_bf16 v[62:65], v[146:149], v[204:207], v[62:65]
	v_mfma_f32_16x16x32_bf16 v[58:61], v[160:163], v[204:207], v[58:61]
	v_mfma_f32_16x16x32_bf16 v[46:49], v[146:149], v[212:215], v[46:49]
	v_mfma_f32_16x16x32_bf16 v[42:45], v[160:163], v[212:215], v[42:45]
	v_mfma_f32_16x16x32_bf16 v[30:33], v[146:149], v[220:223], v[30:33]
	v_mfma_f32_16x16x32_bf16 v[26:29], v[160:163], v[220:223], v[26:29]
	v_mfma_f32_16x16x32_bf16 v[14:17], v[146:149], v[228:231], v[14:17]
	v_mfma_f32_16x16x32_bf16 v[10:13], v[160:163], v[228:231], v[10:13]
	v_mfma_f32_16x16x32_bf16 v[54:57], v[164:167], v[180:183], v[54:57]
	v_mfma_f32_16x16x32_bf16 v[50:53], v[172:175], v[180:183], v[50:53]
	v_mfma_f32_16x16x32_bf16 v[38:41], v[164:167], v[208:211], v[38:41]
	v_mfma_f32_16x16x32_bf16 v[34:37], v[172:175], v[208:211], v[34:37]
	v_mfma_f32_16x16x32_bf16 v[22:25], v[164:167], v[216:219], v[22:25]
	v_mfma_f32_16x16x32_bf16 v[18:21], v[172:175], v[216:219], v[18:21]
	v_mfma_f32_16x16x32_bf16 v[6:9], v[164:167], v[224:227], v[6:9]
	v_mfma_f32_16x16x32_bf16 v[2:5], v[172:175], v[224:227], v[2:5]
	v_mfma_f32_16x16x32_bf16 v[54:57], v[168:171], v[204:207], v[54:57]
	v_mfma_f32_16x16x32_bf16 v[50:53], v[176:179], v[204:207], v[50:53]
	v_mfma_f32_16x16x32_bf16 v[38:41], v[168:171], v[212:215], v[38:41]
	v_mfma_f32_16x16x32_bf16 v[34:37], v[176:179], v[212:215], v[34:37]
	v_mfma_f32_16x16x32_bf16 v[22:25], v[168:171], v[220:223], v[22:25]
	v_mfma_f32_16x16x32_bf16 v[18:21], v[176:179], v[220:223], v[18:21]
	v_mfma_f32_16x16x32_bf16 v[6:9], v[168:171], v[228:231], v[6:9]
	v_mfma_f32_16x16x32_bf16 v[2:5], v[176:179], v[228:231], v[2:5]
	s_barrier
	s_setprio 0
	s_add_i32 s67, 0, 0x18000
	v_add_u32_e32 v0, s67, v158
	s_add_i32 s68, 0, 0x1c000
	ds_read_b128 v[142:145], v0
	ds_read_b128 v[146:149], v0 offset:1024
	ds_read_b128 v[150:153], v0 offset:2048
	ds_read_b128 v[160:163], v0 offset:3072
	v_add_u32_e32 v0, s68, v158
	ds_read_b128 v[164:167], v0
	ds_read_b128 v[168:171], v0 offset:1024
	ds_read_b128 v[172:175], v0 offset:2048
	ds_read_b128 v[176:179], v0 offset:3072
	s_add_u32 s56, s56, 0x40000
	s_addc_u32 s57, s57, 0
	s_mov_b32 m0, s61
	ds_read_b128 v[180:183], v159 offset:32768
	ds_read_b128 v[204:207], v159 offset:33792
	ds_read_b128 v[208:211], v159 offset:34816
	ds_read_b128 v[212:215], v159 offset:35840
	ds_read_b128 v[216:219], v159 offset:36864
	ds_read_b128 v[220:223], v159 offset:37888
	ds_read_b128 v[224:227], v159 offset:38912
	ds_read_b128 v[228:231], v159 offset:39936
	global_load_lds_dwordx4 v136, s[56:57]
	s_mov_b32 m0, s62
	s_nop 0
	global_load_lds_dwordx4 v132, s[56:57]
	s_waitcnt vmcnt(8)
	s_waitcnt lgkmcnt(0)
	s_setprio 1
	s_barrier
	v_mfma_f32_16x16x32_bf16 v[126:129], v[142:145], v[180:183], v[126:129]
	v_mfma_f32_16x16x32_bf16 v[122:125], v[150:153], v[180:183], v[122:125]
	v_mfma_f32_16x16x32_bf16 v[110:113], v[142:145], v[208:211], v[110:113]
	v_mfma_f32_16x16x32_bf16 v[106:109], v[150:153], v[208:211], v[106:109]
	v_mfma_f32_16x16x32_bf16 v[94:97], v[142:145], v[216:219], v[94:97]
	v_mfma_f32_16x16x32_bf16 v[90:93], v[150:153], v[216:219], v[90:93]
	v_mfma_f32_16x16x32_bf16 v[78:81], v[142:145], v[224:227], v[78:81]
	v_mfma_f32_16x16x32_bf16 v[74:77], v[150:153], v[224:227], v[74:77]
	v_mfma_f32_16x16x32_bf16 v[126:129], v[146:149], v[204:207], v[126:129]
	v_mfma_f32_16x16x32_bf16 v[122:125], v[160:163], v[204:207], v[122:125]
	v_mfma_f32_16x16x32_bf16 v[110:113], v[146:149], v[212:215], v[110:113]
	v_mfma_f32_16x16x32_bf16 v[106:109], v[160:163], v[212:215], v[106:109]
	v_mfma_f32_16x16x32_bf16 v[94:97], v[146:149], v[220:223], v[94:97]
	v_mfma_f32_16x16x32_bf16 v[90:93], v[160:163], v[220:223], v[90:93]
	v_mfma_f32_16x16x32_bf16 v[78:81], v[146:149], v[228:231], v[78:81]
	v_mfma_f32_16x16x32_bf16 v[74:77], v[160:163], v[228:231], v[74:77]
	v_mfma_f32_16x16x32_bf16 v[118:121], v[164:167], v[180:183], v[118:121]
	v_mfma_f32_16x16x32_bf16 v[114:117], v[172:175], v[180:183], v[114:117]
	v_mfma_f32_16x16x32_bf16 v[102:105], v[164:167], v[208:211], v[102:105]
	v_mfma_f32_16x16x32_bf16 v[98:101], v[172:175], v[208:211], v[98:101]
	v_mfma_f32_16x16x32_bf16 v[86:89], v[164:167], v[216:219], v[86:89]
	v_mfma_f32_16x16x32_bf16 v[82:85], v[172:175], v[216:219], v[82:85]
	v_mfma_f32_16x16x32_bf16 v[70:73], v[164:167], v[224:227], v[70:73]
	v_mfma_f32_16x16x32_bf16 v[66:69], v[172:175], v[224:227], v[66:69]
	v_mfma_f32_16x16x32_bf16 v[118:121], v[168:171], v[204:207], v[118:121]
	v_mfma_f32_16x16x32_bf16 v[114:117], v[176:179], v[204:207], v[114:117]
	v_mfma_f32_16x16x32_bf16 v[102:105], v[168:171], v[212:215], v[102:105]
	v_mfma_f32_16x16x32_bf16 v[98:101], v[176:179], v[212:215], v[98:101]
	v_mfma_f32_16x16x32_bf16 v[86:89], v[168:171], v[220:223], v[86:89]
	v_mfma_f32_16x16x32_bf16 v[82:85], v[176:179], v[220:223], v[82:85]
	v_mfma_f32_16x16x32_bf16 v[70:73], v[168:171], v[228:231], v[70:73]
	v_mfma_f32_16x16x32_bf16 v[66:69], v[176:179], v[228:231], v[66:69]
	s_barrier
	s_setprio 0
	s_add_i32 s69, s67, s58
	s_add_u32 s54, s54, 0x80
	s_addc_u32 s55, s55, 0
	s_mov_b32 m0, s69
	ds_read_b128 v[180:183], v159 offset:49152
	ds_read_b128 v[204:207], v159 offset:50176
	ds_read_b128 v[208:211], v159 offset:51200
	ds_read_b128 v[212:215], v159 offset:52224
	ds_read_b128 v[216:219], v159 offset:53248
	ds_read_b128 v[220:223], v159 offset:54272
	ds_read_b128 v[224:227], v159 offset:55296
	ds_read_b128 v[228:231], v159 offset:56320
	global_load_lds_dwordx4 v134, s[54:55]
	s_add_i32 m0, s69, 0x2000
	s_add_i32 s69, s68, s58
	global_load_lds_dwordx4 v130, s[54:55]
	s_add_u32 s54, s54, 0x40000
	s_addc_u32 s55, s55, 0
	s_mov_b32 m0, s69
	s_sub_u32 s56, s56, 0x3ff80
	global_load_lds_dwordx4 v134, s[54:55]
	s_subb_u32 s57, s57, 0
	s_add_i32 m0, s69, 0x2000
	s_nop 0
	global_load_lds_dwordx4 v130, s[54:55]
	s_mov_b32 m0, s5
	s_nop 0
	global_load_lds_dwordx4 v136, s[56:57]
	s_mov_b32 m0, s6
	s_nop 0
	global_load_lds_dwordx4 v132, s[56:57]
	s_waitcnt vmcnt(8)
	s_waitcnt lgkmcnt(0)
	s_setprio 1
	s_barrier
	v_mfma_f32_16x16x32_bf16 v[62:65], v[142:145], v[180:183], v[62:65]
	v_mfma_f32_16x16x32_bf16 v[58:61], v[150:153], v[180:183], v[58:61]
	v_mfma_f32_16x16x32_bf16 v[46:49], v[142:145], v[208:211], v[46:49]
	v_mfma_f32_16x16x32_bf16 v[42:45], v[150:153], v[208:211], v[42:45]
	v_mfma_f32_16x16x32_bf16 v[30:33], v[142:145], v[216:219], v[30:33]
	v_mfma_f32_16x16x32_bf16 v[26:29], v[150:153], v[216:219], v[26:29]
	v_mfma_f32_16x16x32_bf16 v[14:17], v[142:145], v[224:227], v[14:17]
	v_mfma_f32_16x16x32_bf16 v[10:13], v[150:153], v[224:227], v[10:13]
	v_mfma_f32_16x16x32_bf16 v[62:65], v[146:149], v[204:207], v[62:65]
	v_mfma_f32_16x16x32_bf16 v[58:61], v[160:163], v[204:207], v[58:61]
	v_mfma_f32_16x16x32_bf16 v[46:49], v[146:149], v[212:215], v[46:49]
	v_mfma_f32_16x16x32_bf16 v[42:45], v[160:163], v[212:215], v[42:45]
	v_mfma_f32_16x16x32_bf16 v[30:33], v[146:149], v[220:223], v[30:33]
	v_mfma_f32_16x16x32_bf16 v[26:29], v[160:163], v[220:223], v[26:29]
	v_mfma_f32_16x16x32_bf16 v[14:17], v[146:149], v[228:231], v[14:17]
	v_mfma_f32_16x16x32_bf16 v[10:13], v[160:163], v[228:231], v[10:13]
	v_mfma_f32_16x16x32_bf16 v[54:57], v[164:167], v[180:183], v[54:57]
	v_mfma_f32_16x16x32_bf16 v[50:53], v[172:175], v[180:183], v[50:53]
	v_mfma_f32_16x16x32_bf16 v[38:41], v[164:167], v[208:211], v[38:41]
	v_mfma_f32_16x16x32_bf16 v[34:37], v[172:175], v[208:211], v[34:37]
	v_mfma_f32_16x16x32_bf16 v[22:25], v[164:167], v[216:219], v[22:25]
	v_mfma_f32_16x16x32_bf16 v[18:21], v[172:175], v[216:219], v[18:21]
	v_mfma_f32_16x16x32_bf16 v[6:9], v[164:167], v[224:227], v[6:9]
	v_mfma_f32_16x16x32_bf16 v[2:5], v[172:175], v[224:227], v[2:5]
	v_mfma_f32_16x16x32_bf16 v[54:57], v[168:171], v[204:207], v[54:57]
	v_mfma_f32_16x16x32_bf16 v[50:53], v[176:179], v[204:207], v[50:53]
	v_mfma_f32_16x16x32_bf16 v[38:41], v[168:171], v[212:215], v[38:41]
	v_mfma_f32_16x16x32_bf16 v[34:37], v[176:179], v[212:215], v[34:37]
	v_mfma_f32_16x16x32_bf16 v[22:25], v[168:171], v[220:223], v[22:25]
	v_mfma_f32_16x16x32_bf16 v[18:21], v[176:179], v[220:223], v[18:21]
	v_mfma_f32_16x16x32_bf16 v[6:9], v[168:171], v[228:231], v[6:9]
	v_mfma_f32_16x16x32_bf16 v[2:5], v[176:179], v[228:231], v[2:5]
	s_barrier
	s_setprio 0
	s_add_i32 s66, s66, 2
	s_add_u32 s52, s52, 0x100
	s_addc_u32 s53, s53, 0
	s_add_u32 s64, s64, 0x100
	s_addc_u32 s65, s65, 0
	s_cmp_gt_u32 s66, 13
	s_cbranch_scc0 .LBB0_422
	s_and_b64 vcc, exec, s[38:39]
	s_cbranch_vccz .LBB0_425
	s_barrier

.Lrb3_skip:
	s_add_u32 s54, s52, 0xfffc0080
	s_addc_u32 s55, s53, -1
	s_add_i32 s61, 0, 0x10000
	s_cmp_eq_u32 s60, 12
	s_cselect_b32 s57, s19, s55
	s_cselect_b32 s56, s45, s54
	v_add_u32_e32 v0, s61, v160
	s_cselect_b32 s55, s41, s59
	s_cselect_b32 s54, s47, s58
	s_add_i32 s64, 0, 0x14000
	ds_read_b128 v[142:145], v0
	ds_read_b128 v[146:149], v0 offset:1024
	ds_read_b128 v[150:153], v0 offset:2048
	ds_read_b128 v[154:157], v0 offset:3072
	v_add_u32_e32 v0, s64, v160
	ds_read_b128 v[162:165], v0
	ds_read_b128 v[166:169], v0 offset:1024
	ds_read_b128 v[170:173], v0 offset:2048
	ds_read_b128 v[174:177], v0 offset:3072
	s_add_i32 m0, s71, 0xc000
	ds_read_b128 v[178:181], v161
	ds_read_b128 v[182:185], v161 offset:1024
	ds_read_b128 v[204:207], v161 offset:2048
	ds_read_b128 v[208:211], v161 offset:3072
	ds_read_b128 v[212:215], v161 offset:4096
	ds_read_b128 v[216:219], v161 offset:5120
	ds_read_b128 v[220:223], v161 offset:6144
	ds_read_b128 v[224:227], v161 offset:7168
	global_load_lds_dwordx4 v138, s[52:53]
	s_add_i32 m0, s71, 0xe000
	s_nop 0
	global_load_lds_dwordx4 v140, s[52:53]
	s_waitcnt vmcnt(8)
	s_waitcnt lgkmcnt(0)
	s_setprio 1
	s_barrier
	v_mfma_f32_16x16x32_bf16 v[126:129], v[142:145], v[178:181], 0
	v_mfma_f32_16x16x32_bf16 v[122:125], v[150:153], v[178:181], 0
	v_mfma_f32_16x16x32_bf16 v[110:113], v[142:145], v[204:207], 0
	v_mfma_f32_16x16x32_bf16 v[106:109], v[150:153], v[204:207], 0
	v_mfma_f32_16x16x32_bf16 v[94:97], v[142:145], v[212:215], 0
	v_mfma_f32_16x16x32_bf16 v[90:93], v[150:153], v[212:215], 0
	v_mfma_f32_16x16x32_bf16 v[78:81], v[142:145], v[220:223], 0
	v_mfma_f32_16x16x32_bf16 v[74:77], v[150:153], v[220:223], 0
	v_mfma_f32_16x16x32_bf16 v[126:129], v[146:149], v[182:185], v[126:129]
	v_mfma_f32_16x16x32_bf16 v[122:125], v[154:157], v[182:185], v[122:125]
	v_mfma_f32_16x16x32_bf16 v[110:113], v[146:149], v[208:211], v[110:113]
	v_mfma_f32_16x16x32_bf16 v[106:109], v[154:157], v[208:211], v[106:109]
	v_mfma_f32_16x16x32_bf16 v[94:97], v[146:149], v[216:219], v[94:97]
	v_mfma_f32_16x16x32_bf16 v[90:93], v[154:157], v[216:219], v[90:93]
	v_mfma_f32_16x16x32_bf16 v[78:81], v[146:149], v[224:227], v[78:81]
	v_mfma_f32_16x16x32_bf16 v[74:77], v[154:157], v[224:227], v[74:77]
	v_mfma_f32_16x16x32_bf16 v[118:121], v[162:165], v[178:181], 0
	v_mfma_f32_16x16x32_bf16 v[114:117], v[170:173], v[178:181], 0
	v_mfma_f32_16x16x32_bf16 v[102:105], v[162:165], v[204:207], 0
	v_mfma_f32_16x16x32_bf16 v[98:101], v[170:173], v[204:207], 0
	v_mfma_f32_16x16x32_bf16 v[86:89], v[162:165], v[212:215], 0
	v_mfma_f32_16x16x32_bf16 v[82:85], v[170:173], v[212:215], 0
	v_mfma_f32_16x16x32_bf16 v[70:73], v[162:165], v[220:223], 0
	v_mfma_f32_16x16x32_bf16 v[66:69], v[170:173], v[220:223], 0
	v_mfma_f32_16x16x32_bf16 v[118:121], v[166:169], v[182:185], v[118:121]
	v_mfma_f32_16x16x32_bf16 v[114:117], v[174:177], v[182:185], v[114:117]
	v_mfma_f32_16x16x32_bf16 v[102:105], v[166:169], v[208:211], v[102:105]
	v_mfma_f32_16x16x32_bf16 v[98:101], v[174:177], v[208:211], v[98:101]
	v_mfma_f32_16x16x32_bf16 v[86:89], v[166:169], v[216:219], v[86:89]
	v_mfma_f32_16x16x32_bf16 v[82:85], v[174:177], v[216:219], v[82:85]
	v_mfma_f32_16x16x32_bf16 v[70:73], v[166:169], v[224:227], v[70:73]
	v_mfma_f32_16x16x32_bf16 v[66:69], v[174:177], v[224:227], v[66:69]
	s_barrier
	s_setprio 0
	s_add_i32 s61, s61, s70
	s_mov_b32 m0, s61
	ds_read_b128 v[178:181], v161 offset:16384
	ds_read_b128 v[182:185], v161 offset:17408
	ds_read_b128 v[204:207], v161 offset:18432
	ds_read_b128 v[208:211], v161 offset:19456
	ds_read_b128 v[212:215], v161 offset:20480
	ds_read_b128 v[216:219], v161 offset:21504
	ds_read_b128 v[220:223], v161 offset:22528
	ds_read_b128 v[224:227], v161 offset:23552
	global_load_lds_dwordx4 v134, s[54:55]
	s_add_i32 m0, s61, 0x2000
	s_add_u32 s62, s54, 0x40000
	s_addc_u32 s63, s55, 0
	s_add_i32 s61, s64, s70
	global_load_lds_dwordx4 v130, s[54:55]
	s_mov_b32 m0, s61
	s_nop 0
	global_load_lds_dwordx4 v134, s[62:63]
	s_add_i32 m0, s61, 0x2000
	s_nop 0
	global_load_lds_dwordx4 v130, s[62:63]
	s_mov_b32 m0, s71
	s_nop 0
	global_load_lds_dwordx4 v136, s[56:57]
	s_mov_b32 m0, s72
	s_nop 0
	global_load_lds_dwordx4 v132, s[56:57]
	s_waitcnt vmcnt(8)
	s_waitcnt lgkmcnt(0)
	s_setprio 1
	s_barrier
	v_mfma_f32_16x16x32_bf16 v[62:65], v[142:145], v[178:181], 0
	v_mfma_f32_16x16x32_bf16 v[58:61], v[150:153], v[178:181], 0
	v_mfma_f32_16x16x32_bf16 v[46:49], v[142:145], v[204:207], 0
	v_mfma_f32_16x16x32_bf16 v[42:45], v[150:153], v[204:207], 0
	v_mfma_f32_16x16x32_bf16 v[30:33], v[142:145], v[212:215], 0
	v_mfma_f32_16x16x32_bf16 v[26:29], v[150:153], v[212:215], 0
	v_mfma_f32_16x16x32_bf16 v[14:17], v[142:145], v[220:223], 0
	v_mfma_f32_16x16x32_bf16 v[10:13], v[150:153], v[220:223], 0
	v_mfma_f32_16x16x32_bf16 v[62:65], v[146:149], v[182:185], v[62:65]
	v_mfma_f32_16x16x32_bf16 v[58:61], v[154:157], v[182:185], v[58:61]
	v_mfma_f32_16x16x32_bf16 v[46:49], v[146:149], v[208:211], v[46:49]
	v_mfma_f32_16x16x32_bf16 v[42:45], v[154:157], v[208:211], v[42:45]
	v_mfma_f32_16x16x32_bf16 v[30:33], v[146:149], v[216:219], v[30:33]
	v_mfma_f32_16x16x32_bf16 v[26:29], v[154:157], v[216:219], v[26:29]
	v_mfma_f32_16x16x32_bf16 v[14:17], v[146:149], v[224:227], v[14:17]
	v_mfma_f32_16x16x32_bf16 v[10:13], v[154:157], v[224:227], v[10:13]
	v_mfma_f32_16x16x32_bf16 v[54:57], v[162:165], v[178:181], 0
	v_mfma_f32_16x16x32_bf16 v[50:53], v[170:173], v[178:181], 0
	v_mfma_f32_16x16x32_bf16 v[38:41], v[162:165], v[204:207], 0
	v_mfma_f32_16x16x32_bf16 v[34:37], v[170:173], v[204:207], 0
	v_mfma_f32_16x16x32_bf16 v[22:25], v[162:165], v[212:215], 0
	v_mfma_f32_16x16x32_bf16 v[18:21], v[170:173], v[212:215], 0
	v_mfma_f32_16x16x32_bf16 v[6:9], v[162:165], v[220:223], 0
	v_mfma_f32_16x16x32_bf16 v[2:5], v[170:173], v[220:223], 0
	v_mfma_f32_16x16x32_bf16 v[54:57], v[166:169], v[182:185], v[54:57]
	v_mfma_f32_16x16x32_bf16 v[50:53], v[174:177], v[182:185], v[50:53]
	v_mfma_f32_16x16x32_bf16 v[38:41], v[166:169], v[208:211], v[38:41]
	v_mfma_f32_16x16x32_bf16 v[34:37], v[174:177], v[208:211], v[34:37]
	v_mfma_f32_16x16x32_bf16 v[22:25], v[166:169], v[216:219], v[22:25]
	v_mfma_f32_16x16x32_bf16 v[18:21], v[174:177], v[216:219], v[18:21]
	v_mfma_f32_16x16x32_bf16 v[6:9], v[166:169], v[224:227], v[6:9]
	v_mfma_f32_16x16x32_bf16 v[2:5], v[174:177], v[224:227], v[2:5]
	s_barrier
	s_setprio 0
	s_add_i32 s61, 0, 0x18000
	v_add_u32_e32 v0, s61, v160
	s_add_i32 s62, 0, 0x1c000
	ds_read_b128 v[142:145], v0
	ds_read_b128 v[146:149], v0 offset:1024
	ds_read_b128 v[150:153], v0 offset:2048
	ds_read_b128 v[154:157], v0 offset:3072
	v_add_u32_e32 v0, s62, v160
	ds_read_b128 v[162:165], v0
	ds_read_b128 v[166:169], v0 offset:1024
	ds_read_b128 v[170:173], v0 offset:2048
	ds_read_b128 v[174:177], v0 offset:3072
	s_add_u32 s56, s56, 0x40000
	s_addc_u32 s57, s57, 0
	s_mov_b32 m0, s73
	ds_read_b128 v[178:181], v161 offset:32768
	ds_read_b128 v[182:185], v161 offset:33792
	ds_read_b128 v[204:207], v161 offset:34816
	ds_read_b128 v[208:211], v161 offset:35840
	ds_read_b128 v[212:215], v161 offset:36864
	ds_read_b128 v[216:219], v161 offset:37888
	ds_read_b128 v[220:223], v161 offset:38912
	ds_read_b128 v[224:227], v161 offset:39936
	global_load_lds_dwordx4 v136, s[56:57]
	s_mov_b32 m0, s74
	s_nop 0
	global_load_lds_dwordx4 v132, s[56:57]
	s_waitcnt vmcnt(8)
	s_waitcnt lgkmcnt(0)
	s_setprio 1
	s_barrier
	v_mfma_f32_16x16x32_bf16 v[126:129], v[142:145], v[178:181], v[126:129]
	v_mfma_f32_16x16x32_bf16 v[122:125], v[150:153], v[178:181], v[122:125]
	v_mfma_f32_16x16x32_bf16 v[110:113], v[142:145], v[204:207], v[110:113]
	v_mfma_f32_16x16x32_bf16 v[106:109], v[150:153], v[204:207], v[106:109]
	v_mfma_f32_16x16x32_bf16 v[94:97], v[142:145], v[212:215], v[94:97]
	v_mfma_f32_16x16x32_bf16 v[90:93], v[150:153], v[212:215], v[90:93]
	v_mfma_f32_16x16x32_bf16 v[78:81], v[142:145], v[220:223], v[78:81]
	v_mfma_f32_16x16x32_bf16 v[74:77], v[150:153], v[220:223], v[74:77]
	v_mfma_f32_16x16x32_bf16 v[126:129], v[146:149], v[182:185], v[126:129]
	v_mfma_f32_16x16x32_bf16 v[122:125], v[154:157], v[182:185], v[122:125]
	v_mfma_f32_16x16x32_bf16 v[110:113], v[146:149], v[208:211], v[110:113]
	v_mfma_f32_16x16x32_bf16 v[106:109], v[154:157], v[208:211], v[106:109]
	v_mfma_f32_16x16x32_bf16 v[94:97], v[146:149], v[216:219], v[94:97]
	v_mfma_f32_16x16x32_bf16 v[90:93], v[154:157], v[216:219], v[90:93]
	v_mfma_f32_16x16x32_bf16 v[78:81], v[146:149], v[224:227], v[78:81]
	v_mfma_f32_16x16x32_bf16 v[74:77], v[154:157], v[224:227], v[74:77]
	v_mfma_f32_16x16x32_bf16 v[118:121], v[162:165], v[178:181], v[118:121]
	v_mfma_f32_16x16x32_bf16 v[114:117], v[170:173], v[178:181], v[114:117]
	v_mfma_f32_16x16x32_bf16 v[102:105], v[162:165], v[204:207], v[102:105]
	v_mfma_f32_16x16x32_bf16 v[98:101], v[170:173], v[204:207], v[98:101]
	v_mfma_f32_16x16x32_bf16 v[86:89], v[162:165], v[212:215], v[86:89]
	v_mfma_f32_16x16x32_bf16 v[82:85], v[170:173], v[212:215], v[82:85]
	v_mfma_f32_16x16x32_bf16 v[70:73], v[162:165], v[220:223], v[70:73]
	v_mfma_f32_16x16x32_bf16 v[66:69], v[170:173], v[220:223], v[66:69]
	v_mfma_f32_16x16x32_bf16 v[118:121], v[166:169], v[182:185], v[118:121]
	v_mfma_f32_16x16x32_bf16 v[114:117], v[174:177], v[182:185], v[114:117]
	v_mfma_f32_16x16x32_bf16 v[102:105], v[166:169], v[208:211], v[102:105]
	v_mfma_f32_16x16x32_bf16 v[98:101], v[174:177], v[208:211], v[98:101]
	v_mfma_f32_16x16x32_bf16 v[86:89], v[166:169], v[216:219], v[86:89]
	v_mfma_f32_16x16x32_bf16 v[82:85], v[174:177], v[216:219], v[82:85]
	v_mfma_f32_16x16x32_bf16 v[70:73], v[166:169], v[224:227], v[70:73]
	v_mfma_f32_16x16x32_bf16 v[66:69], v[174:177], v[224:227], v[66:69]
	s_barrier
	s_setprio 0
	s_add_i32 s63, s61, s70
	s_add_u32 s54, s54, 0x80
	s_addc_u32 s55, s55, 0
	s_mov_b32 m0, s63
	ds_read_b128 v[178:181], v161 offset:49152
	ds_read_b128 v[182:185], v161 offset:50176
	ds_read_b128 v[204:207], v161 offset:51200
	ds_read_b128 v[208:211], v161 offset:52224
	ds_read_b128 v[212:215], v161 offset:53248
	ds_read_b128 v[216:219], v161 offset:54272
	ds_read_b128 v[220:223], v161 offset:55296
	ds_read_b128 v[224:227], v161 offset:56320
	global_load_lds_dwordx4 v134, s[54:55]
	s_add_i32 m0, s63, 0x2000
	s_add_i32 s63, s62, s70
	global_load_lds_dwordx4 v130, s[54:55]
	s_add_u32 s54, s54, 0x40000
	s_addc_u32 s55, s55, 0
	s_mov_b32 m0, s63
	s_sub_u32 s56, s56, 0x3ff80
	global_load_lds_dwordx4 v134, s[54:55]
	s_subb_u32 s57, s57, 0
	s_add_i32 m0, s63, 0x2000
	s_nop 0
	global_load_lds_dwordx4 v130, s[54:55]
	s_mov_b32 m0, s86
	s_nop 0
	global_load_lds_dwordx4 v136, s[56:57]
	s_mov_b32 m0, s87
	s_nop 0
	global_load_lds_dwordx4 v132, s[56:57]
	s_waitcnt vmcnt(8)
	s_waitcnt lgkmcnt(0)
	s_setprio 1
	s_barrier
	v_mfma_f32_16x16x32_bf16 v[62:65], v[142:145], v[178:181], v[62:65]
	v_mfma_f32_16x16x32_bf16 v[58:61], v[150:153], v[178:181], v[58:61]
	v_mfma_f32_16x16x32_bf16 v[46:49], v[142:145], v[204:207], v[46:49]
	v_mfma_f32_16x16x32_bf16 v[42:45], v[150:153], v[204:207], v[42:45]
	v_mfma_f32_16x16x32_bf16 v[30:33], v[142:145], v[212:215], v[30:33]
	v_mfma_f32_16x16x32_bf16 v[26:29], v[150:153], v[212:215], v[26:29]
	v_mfma_f32_16x16x32_bf16 v[14:17], v[142:145], v[220:223], v[14:17]
	v_mfma_f32_16x16x32_bf16 v[10:13], v[150:153], v[220:223], v[10:13]
	v_mfma_f32_16x16x32_bf16 v[62:65], v[146:149], v[182:185], v[62:65]
	v_mfma_f32_16x16x32_bf16 v[58:61], v[154:157], v[182:185], v[58:61]
	v_mfma_f32_16x16x32_bf16 v[46:49], v[146:149], v[208:211], v[46:49]
	v_mfma_f32_16x16x32_bf16 v[42:45], v[154:157], v[208:211], v[42:45]
	v_mfma_f32_16x16x32_bf16 v[30:33], v[146:149], v[216:219], v[30:33]
	v_mfma_f32_16x16x32_bf16 v[26:29], v[154:157], v[216:219], v[26:29]
	v_mfma_f32_16x16x32_bf16 v[14:17], v[146:149], v[224:227], v[14:17]
	v_mfma_f32_16x16x32_bf16 v[10:13], v[154:157], v[224:227], v[10:13]
	v_mfma_f32_16x16x32_bf16 v[54:57], v[162:165], v[178:181], v[54:57]
	v_mfma_f32_16x16x32_bf16 v[50:53], v[170:173], v[178:181], v[50:53]
	v_mfma_f32_16x16x32_bf16 v[38:41], v[162:165], v[204:207], v[38:41]
	v_mfma_f32_16x16x32_bf16 v[34:37], v[170:173], v[204:207], v[34:37]
	v_mfma_f32_16x16x32_bf16 v[22:25], v[162:165], v[212:215], v[22:25]
	v_mfma_f32_16x16x32_bf16 v[18:21], v[170:173], v[212:215], v[18:21]
	v_mfma_f32_16x16x32_bf16 v[6:9], v[162:165], v[220:223], v[6:9]
	v_mfma_f32_16x16x32_bf16 v[2:5], v[170:173], v[220:223], v[2:5]
	v_mfma_f32_16x16x32_bf16 v[54:57], v[166:169], v[182:185], v[54:57]
	v_mfma_f32_16x16x32_bf16 v[50:53], v[174:177], v[182:185], v[50:53]
	v_mfma_f32_16x16x32_bf16 v[38:41], v[166:169], v[208:211], v[38:41]
	v_mfma_f32_16x16x32_bf16 v[34:37], v[174:177], v[208:211], v[34:37]
	v_mfma_f32_16x16x32_bf16 v[22:25], v[166:169], v[216:219], v[22:25]
	v_mfma_f32_16x16x32_bf16 v[18:21], v[174:177], v[216:219], v[18:21]
	v_mfma_f32_16x16x32_bf16 v[6:9], v[166:169], v[224:227], v[6:9]
	v_mfma_f32_16x16x32_bf16 v[2:5], v[174:177], v[224:227], v[2:5]
	s_barrier
	s_setprio 0
	s_add_i32 s60, s60, 2
	s_add_u32 s52, s52, 0x100
	s_addc_u32 s53, s53, 0
	s_add_u32 s58, s58, 0x100
	s_addc_u32 s59, s59, 0
	s_cmp_gt_u32 s60, 13
.LBB0_479:
	s_add_u32 s54, s52, 0xfffc0080
	s_addc_u32 s55, s53, -1
	s_add_i32 s61, 0, 0x10000
	s_cmp_eq_u32 s60, 12
	s_cselect_b32 s57, s19, s55
	s_cselect_b32 s56, s45, s54
	v_add_u32_e32 v0, s61, v160
	s_cselect_b32 s55, s41, s59
	s_cselect_b32 s54, s47, s58
	s_add_i32 s64, 0, 0x14000
	ds_read_b128 v[142:145], v0
	ds_read_b128 v[146:149], v0 offset:1024
	ds_read_b128 v[150:153], v0 offset:2048
	ds_read_b128 v[154:157], v0 offset:3072
	v_add_u32_e32 v0, s64, v160
	ds_read_b128 v[162:165], v0
	ds_read_b128 v[166:169], v0 offset:1024
	ds_read_b128 v[170:173], v0 offset:2048
	ds_read_b128 v[174:177], v0 offset:3072
	s_add_i32 m0, s71, 0xc000
	ds_read_b128 v[178:181], v161
	ds_read_b128 v[182:185], v161 offset:1024
	ds_read_b128 v[204:207], v161 offset:2048
	ds_read_b128 v[208:211], v161 offset:3072
	ds_read_b128 v[212:215], v161 offset:4096
	ds_read_b128 v[216:219], v161 offset:5120
	ds_read_b128 v[220:223], v161 offset:6144
	ds_read_b128 v[224:227], v161 offset:7168
	global_load_lds_dwordx4 v138, s[52:53]
	s_add_i32 m0, s71, 0xe000
	s_nop 0
	global_load_lds_dwordx4 v140, s[52:53]
	s_waitcnt vmcnt(8)
	s_waitcnt lgkmcnt(0)
	s_setprio 1
	s_barrier
	v_mfma_f32_16x16x32_bf16 v[126:129], v[142:145], v[178:181], v[126:129]
	v_mfma_f32_16x16x32_bf16 v[122:125], v[150:153], v[178:181], v[122:125]
	v_mfma_f32_16x16x32_bf16 v[110:113], v[142:145], v[204:207], v[110:113]
	v_mfma_f32_16x16x32_bf16 v[106:109], v[150:153], v[204:207], v[106:109]
	v_mfma_f32_16x16x32_bf16 v[94:97], v[142:145], v[212:215], v[94:97]
	v_mfma_f32_16x16x32_bf16 v[90:93], v[150:153], v[212:215], v[90:93]
	v_mfma_f32_16x16x32_bf16 v[78:81], v[142:145], v[220:223], v[78:81]
	v_mfma_f32_16x16x32_bf16 v[74:77], v[150:153], v[220:223], v[74:77]
	v_mfma_f32_16x16x32_bf16 v[126:129], v[146:149], v[182:185], v[126:129]
	v_mfma_f32_16x16x32_bf16 v[122:125], v[154:157], v[182:185], v[122:125]
	v_mfma_f32_16x16x32_bf16 v[110:113], v[146:149], v[208:211], v[110:113]
	v_mfma_f32_16x16x32_bf16 v[106:109], v[154:157], v[208:211], v[106:109]
	v_mfma_f32_16x16x32_bf16 v[94:97], v[146:149], v[216:219], v[94:97]
	v_mfma_f32_16x16x32_bf16 v[90:93], v[154:157], v[216:219], v[90:93]
	v_mfma_f32_16x16x32_bf16 v[78:81], v[146:149], v[224:227], v[78:81]
	v_mfma_f32_16x16x32_bf16 v[74:77], v[154:157], v[224:227], v[74:77]
	v_mfma_f32_16x16x32_bf16 v[118:121], v[162:165], v[178:181], v[118:121]
	v_mfma_f32_16x16x32_bf16 v[114:117], v[170:173], v[178:181], v[114:117]
	v_mfma_f32_16x16x32_bf16 v[102:105], v[162:165], v[204:207], v[102:105]
	v_mfma_f32_16x16x32_bf16 v[98:101], v[170:173], v[204:207], v[98:101]
	v_mfma_f32_16x16x32_bf16 v[86:89], v[162:165], v[212:215], v[86:89]
	v_mfma_f32_16x16x32_bf16 v[82:85], v[170:173], v[212:215], v[82:85]
	v_mfma_f32_16x16x32_bf16 v[70:73], v[162:165], v[220:223], v[70:73]
	v_mfma_f32_16x16x32_bf16 v[66:69], v[170:173], v[220:223], v[66:69]
	v_mfma_f32_16x16x32_bf16 v[118:121], v[166:169], v[182:185], v[118:121]
	v_mfma_f32_16x16x32_bf16 v[114:117], v[174:177], v[182:185], v[114:117]
	v_mfma_f32_16x16x32_bf16 v[102:105], v[166:169], v[208:211], v[102:105]
	v_mfma_f32_16x16x32_bf16 v[98:101], v[174:177], v[208:211], v[98:101]
	v_mfma_f32_16x16x32_bf16 v[86:89], v[166:169], v[216:219], v[86:89]
	v_mfma_f32_16x16x32_bf16 v[82:85], v[174:177], v[216:219], v[82:85]
	v_mfma_f32_16x16x32_bf16 v[70:73], v[166:169], v[224:227], v[70:73]
	v_mfma_f32_16x16x32_bf16 v[66:69], v[174:177], v[224:227], v[66:69]
	s_barrier
	s_setprio 0
	s_add_i32 s61, s61, s70
	s_mov_b32 m0, s61
	ds_read_b128 v[178:181], v161 offset:16384
	ds_read_b128 v[182:185], v161 offset:17408
	ds_read_b128 v[204:207], v161 offset:18432
	ds_read_b128 v[208:211], v161 offset:19456
	ds_read_b128 v[212:215], v161 offset:20480
	ds_read_b128 v[216:219], v161 offset:21504
	ds_read_b128 v[220:223], v161 offset:22528
	ds_read_b128 v[224:227], v161 offset:23552
	global_load_lds_dwordx4 v134, s[54:55]
	s_add_i32 m0, s61, 0x2000
	s_add_u32 s62, s54, 0x40000
	s_addc_u32 s63, s55, 0
	s_add_i32 s61, s64, s70
	global_load_lds_dwordx4 v130, s[54:55]
	s_mov_b32 m0, s61
	s_nop 0
	global_load_lds_dwordx4 v134, s[62:63]
	s_add_i32 m0, s61, 0x2000
	s_nop 0
	global_load_lds_dwordx4 v130, s[62:63]
	s_mov_b32 m0, s71
	s_nop 0
	global_load_lds_dwordx4 v136, s[56:57]
	s_mov_b32 m0, s72
	s_nop 0
	global_load_lds_dwordx4 v132, s[56:57]
	s_waitcnt vmcnt(8)
	s_waitcnt lgkmcnt(0)
	s_setprio 1
	s_barrier
	v_mfma_f32_16x16x32_bf16 v[62:65], v[142:145], v[178:181], v[62:65]
	v_mfma_f32_16x16x32_bf16 v[58:61], v[150:153], v[178:181], v[58:61]
	v_mfma_f32_16x16x32_bf16 v[46:49], v[142:145], v[204:207], v[46:49]
	v_mfma_f32_16x16x32_bf16 v[42:45], v[150:153], v[204:207], v[42:45]
	v_mfma_f32_16x16x32_bf16 v[30:33], v[142:145], v[212:215], v[30:33]
	v_mfma_f32_16x16x32_bf16 v[26:29], v[150:153], v[212:215], v[26:29]
	v_mfma_f32_16x16x32_bf16 v[14:17], v[142:145], v[220:223], v[14:17]
	v_mfma_f32_16x16x32_bf16 v[10:13], v[150:153], v[220:223], v[10:13]
	v_mfma_f32_16x16x32_bf16 v[62:65], v[146:149], v[182:185], v[62:65]
	v_mfma_f32_16x16x32_bf16 v[58:61], v[154:157], v[182:185], v[58:61]
	v_mfma_f32_16x16x32_bf16 v[46:49], v[146:149], v[208:211], v[46:49]
	v_mfma_f32_16x16x32_bf16 v[42:45], v[154:157], v[208:211], v[42:45]
	v_mfma_f32_16x16x32_bf16 v[30:33], v[146:149], v[216:219], v[30:33]
	v_mfma_f32_16x16x32_bf16 v[26:29], v[154:157], v[216:219], v[26:29]
	v_mfma_f32_16x16x32_bf16 v[14:17], v[146:149], v[224:227], v[14:17]
	v_mfma_f32_16x16x32_bf16 v[10:13], v[154:157], v[224:227], v[10:13]
	v_mfma_f32_16x16x32_bf16 v[54:57], v[162:165], v[178:181], v[54:57]
	v_mfma_f32_16x16x32_bf16 v[50:53], v[170:173], v[178:181], v[50:53]
	v_mfma_f32_16x16x32_bf16 v[38:41], v[162:165], v[204:207], v[38:41]
	v_mfma_f32_16x16x32_bf16 v[34:37], v[170:173], v[204:207], v[34:37]
	v_mfma_f32_16x16x32_bf16 v[22:25], v[162:165], v[212:215], v[22:25]
	v_mfma_f32_16x16x32_bf16 v[18:21], v[170:173], v[212:215], v[18:21]
	v_mfma_f32_16x16x32_bf16 v[6:9], v[162:165], v[220:223], v[6:9]
	v_mfma_f32_16x16x32_bf16 v[2:5], v[170:173], v[220:223], v[2:5]
	v_mfma_f32_16x16x32_bf16 v[54:57], v[166:169], v[182:185], v[54:57]
	v_mfma_f32_16x16x32_bf16 v[50:53], v[174:177], v[182:185], v[50:53]
	v_mfma_f32_16x16x32_bf16 v[38:41], v[166:169], v[208:211], v[38:41]
	v_mfma_f32_16x16x32_bf16 v[34:37], v[174:177], v[208:211], v[34:37]
	v_mfma_f32_16x16x32_bf16 v[22:25], v[166:169], v[216:219], v[22:25]
	v_mfma_f32_16x16x32_bf16 v[18:21], v[174:177], v[216:219], v[18:21]
	v_mfma_f32_16x16x32_bf16 v[6:9], v[166:169], v[224:227], v[6:9]
	v_mfma_f32_16x16x32_bf16 v[2:5], v[174:177], v[224:227], v[2:5]
	s_barrier
	s_setprio 0
	s_add_i32 s61, 0, 0x18000
	v_add_u32_e32 v0, s61, v160
	s_add_i32 s62, 0, 0x1c000
	ds_read_b128 v[142:145], v0
	ds_read_b128 v[146:149], v0 offset:1024
	ds_read_b128 v[150:153], v0 offset:2048
	ds_read_b128 v[154:157], v0 offset:3072
	v_add_u32_e32 v0, s62, v160
	ds_read_b128 v[162:165], v0
	ds_read_b128 v[166:169], v0 offset:1024
	ds_read_b128 v[170:173], v0 offset:2048
	ds_read_b128 v[174:177], v0 offset:3072
	s_add_u32 s56, s56, 0x40000
	s_addc_u32 s57, s57, 0
	s_mov_b32 m0, s73
	ds_read_b128 v[178:181], v161 offset:32768
	ds_read_b128 v[182:185], v161 offset:33792
	ds_read_b128 v[204:207], v161 offset:34816
	ds_read_b128 v[208:211], v161 offset:35840
	ds_read_b128 v[212:215], v161 offset:36864
	ds_read_b128 v[216:219], v161 offset:37888
	ds_read_b128 v[220:223], v161 offset:38912
	ds_read_b128 v[224:227], v161 offset:39936
	global_load_lds_dwordx4 v136, s[56:57]
	s_mov_b32 m0, s74
	s_nop 0
	global_load_lds_dwordx4 v132, s[56:57]
	s_waitcnt vmcnt(8)
	s_waitcnt lgkmcnt(0)
	s_setprio 1
	s_barrier
	v_mfma_f32_16x16x32_bf16 v[126:129], v[142:145], v[178:181], v[126:129]
	v_mfma_f32_16x16x32_bf16 v[122:125], v[150:153], v[178:181], v[122:125]
	v_mfma_f32_16x16x32_bf16 v[110:113], v[142:145], v[204:207], v[110:113]
	v_mfma_f32_16x16x32_bf16 v[106:109], v[150:153], v[204:207], v[106:109]
	v_mfma_f32_16x16x32_bf16 v[94:97], v[142:145], v[212:215], v[94:97]
	v_mfma_f32_16x16x32_bf16 v[90:93], v[150:153], v[212:215], v[90:93]
	v_mfma_f32_16x16x32_bf16 v[78:81], v[142:145], v[220:223], v[78:81]
	v_mfma_f32_16x16x32_bf16 v[74:77], v[150:153], v[220:223], v[74:77]
	v_mfma_f32_16x16x32_bf16 v[126:129], v[146:149], v[182:185], v[126:129]
	v_mfma_f32_16x16x32_bf16 v[122:125], v[154:157], v[182:185], v[122:125]
	v_mfma_f32_16x16x32_bf16 v[110:113], v[146:149], v[208:211], v[110:113]
	v_mfma_f32_16x16x32_bf16 v[106:109], v[154:157], v[208:211], v[106:109]
	v_mfma_f32_16x16x32_bf16 v[94:97], v[146:149], v[216:219], v[94:97]
	v_mfma_f32_16x16x32_bf16 v[90:93], v[154:157], v[216:219], v[90:93]
	v_mfma_f32_16x16x32_bf16 v[78:81], v[146:149], v[224:227], v[78:81]
	v_mfma_f32_16x16x32_bf16 v[74:77], v[154:157], v[224:227], v[74:77]
	v_mfma_f32_16x16x32_bf16 v[118:121], v[162:165], v[178:181], v[118:121]
	v_mfma_f32_16x16x32_bf16 v[114:117], v[170:173], v[178:181], v[114:117]
	v_mfma_f32_16x16x32_bf16 v[102:105], v[162:165], v[204:207], v[102:105]
	v_mfma_f32_16x16x32_bf16 v[98:101], v[170:173], v[204:207], v[98:101]
	v_mfma_f32_16x16x32_bf16 v[86:89], v[162:165], v[212:215], v[86:89]
	v_mfma_f32_16x16x32_bf16 v[82:85], v[170:173], v[212:215], v[82:85]
	v_mfma_f32_16x16x32_bf16 v[70:73], v[162:165], v[220:223], v[70:73]
	v_mfma_f32_16x16x32_bf16 v[66:69], v[170:173], v[220:223], v[66:69]
	v_mfma_f32_16x16x32_bf16 v[118:121], v[166:169], v[182:185], v[118:121]
	v_mfma_f32_16x16x32_bf16 v[114:117], v[174:177], v[182:185], v[114:117]
	v_mfma_f32_16x16x32_bf16 v[102:105], v[166:169], v[208:211], v[102:105]
	v_mfma_f32_16x16x32_bf16 v[98:101], v[174:177], v[208:211], v[98:101]
	v_mfma_f32_16x16x32_bf16 v[86:89], v[166:169], v[216:219], v[86:89]
	v_mfma_f32_16x16x32_bf16 v[82:85], v[174:177], v[216:219], v[82:85]
	v_mfma_f32_16x16x32_bf16 v[70:73], v[166:169], v[224:227], v[70:73]
	v_mfma_f32_16x16x32_bf16 v[66:69], v[174:177], v[224:227], v[66:69]
	s_barrier
	s_setprio 0
	s_add_i32 s63, s61, s70
	s_add_u32 s54, s54, 0x80
	s_addc_u32 s55, s55, 0
	s_mov_b32 m0, s63
	ds_read_b128 v[178:181], v161 offset:49152
	ds_read_b128 v[182:185], v161 offset:50176
	ds_read_b128 v[204:207], v161 offset:51200
	ds_read_b128 v[208:211], v161 offset:52224
	ds_read_b128 v[212:215], v161 offset:53248
	ds_read_b128 v[216:219], v161 offset:54272
	ds_read_b128 v[220:223], v161 offset:55296
	ds_read_b128 v[224:227], v161 offset:56320
	global_load_lds_dwordx4 v134, s[54:55]
	s_add_i32 m0, s63, 0x2000
	s_add_i32 s63, s62, s70
	global_load_lds_dwordx4 v130, s[54:55]
	s_add_u32 s54, s54, 0x40000
	s_addc_u32 s55, s55, 0
	s_mov_b32 m0, s63
	s_sub_u32 s56, s56, 0x3ff80
	global_load_lds_dwordx4 v134, s[54:55]
	s_subb_u32 s57, s57, 0
	s_add_i32 m0, s63, 0x2000
	s_nop 0
	global_load_lds_dwordx4 v130, s[54:55]
	s_mov_b32 m0, s86
	s_nop 0
	global_load_lds_dwordx4 v136, s[56:57]
	s_mov_b32 m0, s87
	s_nop 0
	global_load_lds_dwordx4 v132, s[56:57]
	s_waitcnt vmcnt(8)
	s_waitcnt lgkmcnt(0)
	s_setprio 1
	s_barrier
	v_mfma_f32_16x16x32_bf16 v[62:65], v[142:145], v[178:181], v[62:65]
	v_mfma_f32_16x16x32_bf16 v[58:61], v[150:153], v[178:181], v[58:61]
	v_mfma_f32_16x16x32_bf16 v[46:49], v[142:145], v[204:207], v[46:49]
	v_mfma_f32_16x16x32_bf16 v[42:45], v[150:153], v[204:207], v[42:45]
	v_mfma_f32_16x16x32_bf16 v[30:33], v[142:145], v[212:215], v[30:33]
	v_mfma_f32_16x16x32_bf16 v[26:29], v[150:153], v[212:215], v[26:29]
	v_mfma_f32_16x16x32_bf16 v[14:17], v[142:145], v[220:223], v[14:17]
	v_mfma_f32_16x16x32_bf16 v[10:13], v[150:153], v[220:223], v[10:13]
	v_mfma_f32_16x16x32_bf16 v[62:65], v[146:149], v[182:185], v[62:65]
	v_mfma_f32_16x16x32_bf16 v[58:61], v[154:157], v[182:185], v[58:61]
	v_mfma_f32_16x16x32_bf16 v[46:49], v[146:149], v[208:211], v[46:49]
	v_mfma_f32_16x16x32_bf16 v[42:45], v[154:157], v[208:211], v[42:45]
	v_mfma_f32_16x16x32_bf16 v[30:33], v[146:149], v[216:219], v[30:33]
	v_mfma_f32_16x16x32_bf16 v[26:29], v[154:157], v[216:219], v[26:29]
	v_mfma_f32_16x16x32_bf16 v[14:17], v[146:149], v[224:227], v[14:17]
	v_mfma_f32_16x16x32_bf16 v[10:13], v[154:157], v[224:227], v[10:13]
	v_mfma_f32_16x16x32_bf16 v[54:57], v[162:165], v[178:181], v[54:57]
	v_mfma_f32_16x16x32_bf16 v[50:53], v[170:173], v[178:181], v[50:53]
	v_mfma_f32_16x16x32_bf16 v[38:41], v[162:165], v[204:207], v[38:41]
	v_mfma_f32_16x16x32_bf16 v[34:37], v[170:173], v[204:207], v[34:37]
	v_mfma_f32_16x16x32_bf16 v[22:25], v[162:165], v[212:215], v[22:25]
	v_mfma_f32_16x16x32_bf16 v[18:21], v[170:173], v[212:215], v[18:21]
	v_mfma_f32_16x16x32_bf16 v[6:9], v[162:165], v[220:223], v[6:9]
	v_mfma_f32_16x16x32_bf16 v[2:5], v[170:173], v[220:223], v[2:5]
	v_mfma_f32_16x16x32_bf16 v[54:57], v[166:169], v[182:185], v[54:57]
	v_mfma_f32_16x16x32_bf16 v[50:53], v[174:177], v[182:185], v[50:53]
	v_mfma_f32_16x16x32_bf16 v[38:41], v[166:169], v[208:211], v[38:41]
	v_mfma_f32_16x16x32_bf16 v[34:37], v[174:177], v[208:211], v[34:37]
	v_mfma_f32_16x16x32_bf16 v[22:25], v[166:169], v[216:219], v[22:25]
	v_mfma_f32_16x16x32_bf16 v[18:21], v[174:177], v[216:219], v[18:21]
	v_mfma_f32_16x16x32_bf16 v[6:9], v[166:169], v[224:227], v[6:9]
	v_mfma_f32_16x16x32_bf16 v[2:5], v[174:177], v[224:227], v[2:5]
	s_barrier
	s_setprio 0
	s_add_i32 s60, s60, 2
	s_add_u32 s52, s52, 0x100
	s_addc_u32 s53, s53, 0
	s_add_u32 s58, s58, 0x100
	s_addc_u32 s59, s59, 0
	s_cmp_gt_u32 s60, 13
	s_cbranch_scc0 .LBB0_479
	s_and_b64 vcc, exec, s[38:39]
	s_cbranch_vccz .LBB0_482
	s_barrier

.Lrb5_skip:
	s_add_u32 s52, s50, 0xfffc0080
	s_addc_u32 s53, s51, -1
	s_add_i32 s67, 0, 0x10000
	s_cmp_eq_u32 s66, 12
	s_cselect_b32 s55, s45, s53
	s_cselect_b32 s54, s62, s52
	v_add_u32_e32 v0, s67, v144
	s_cselect_b32 s53, s43, s65
	s_cselect_b32 s52, s63, s64
	s_add_i32 s70, 0, 0x14000
	ds_read_b128 v[146:149], v0
	ds_read_b128 v[150:153], v0 offset:1024
	ds_read_b128 v[154:157], v0 offset:2048
	ds_read_b128 v[158:161], v0 offset:3072
	v_add_u32_e32 v0, s70, v144
	ds_read_b128 v[162:165], v0
	ds_read_b128 v[166:169], v0 offset:1024
	ds_read_b128 v[170:173], v0 offset:2048
	ds_read_b128 v[174:177], v0 offset:3072
	s_add_i32 m0, s5, 0xc000
	ds_read_b128 v[178:181], v145
	ds_read_b128 v[182:185], v145 offset:1024
	ds_read_b128 v[204:207], v145 offset:2048
	ds_read_b128 v[208:211], v145 offset:3072
	ds_read_b128 v[212:215], v145 offset:4096
	ds_read_b128 v[220:223], v145 offset:5120
	ds_read_b128 v[224:227], v145 offset:6144
	ds_read_b128 v[228:231], v145 offset:7168
	global_load_lds_dwordx4 v138, s[50:51]
	s_add_i32 m0, s5, 0xe000
	s_nop 0
	global_load_lds_dwordx4 v140, s[50:51]
	s_waitcnt vmcnt(8)
	s_waitcnt lgkmcnt(0)
	s_setprio 1
	s_barrier
	v_mfma_f32_16x16x32_bf16 v[118:121], v[146:149], v[178:181], 0
	v_mfma_f32_16x16x32_bf16 v[114:117], v[154:157], v[178:181], 0
	v_mfma_f32_16x16x32_bf16 v[110:113], v[146:149], v[204:207], 0
	v_mfma_f32_16x16x32_bf16 v[102:105], v[154:157], v[204:207], 0
	v_mfma_f32_16x16x32_bf16 v[94:97], v[146:149], v[212:215], 0
	v_mfma_f32_16x16x32_bf16 v[86:89], v[154:157], v[212:215], 0
	v_mfma_f32_16x16x32_bf16 v[78:81], v[146:149], v[224:227], 0
	v_mfma_f32_16x16x32_bf16 v[70:73], v[154:157], v[224:227], 0
	v_mfma_f32_16x16x32_bf16 v[118:121], v[150:153], v[182:185], v[118:121]
	v_mfma_f32_16x16x32_bf16 v[114:117], v[158:161], v[182:185], v[114:117]
	v_mfma_f32_16x16x32_bf16 v[110:113], v[150:153], v[208:211], v[110:113]
	v_mfma_f32_16x16x32_bf16 v[102:105], v[158:161], v[208:211], v[102:105]
	v_mfma_f32_16x16x32_bf16 v[94:97], v[150:153], v[220:223], v[94:97]
	v_mfma_f32_16x16x32_bf16 v[86:89], v[158:161], v[220:223], v[86:89]
	v_mfma_f32_16x16x32_bf16 v[78:81], v[150:153], v[228:231], v[78:81]
	v_mfma_f32_16x16x32_bf16 v[70:73], v[158:161], v[228:231], v[70:73]
	v_mfma_f32_16x16x32_bf16 v[126:129], v[162:165], v[178:181], 0
	v_mfma_f32_16x16x32_bf16 v[122:125], v[170:173], v[178:181], 0
	v_mfma_f32_16x16x32_bf16 v[106:109], v[162:165], v[204:207], 0
	v_mfma_f32_16x16x32_bf16 v[98:101], v[170:173], v[204:207], 0
	v_mfma_f32_16x16x32_bf16 v[90:93], v[162:165], v[212:215], 0
	v_mfma_f32_16x16x32_bf16 v[82:85], v[170:173], v[212:215], 0
	v_mfma_f32_16x16x32_bf16 v[74:77], v[162:165], v[224:227], 0
	v_mfma_f32_16x16x32_bf16 v[66:69], v[170:173], v[224:227], 0
	v_mfma_f32_16x16x32_bf16 v[126:129], v[166:169], v[182:185], v[126:129]
	v_mfma_f32_16x16x32_bf16 v[122:125], v[174:177], v[182:185], v[122:125]
	v_mfma_f32_16x16x32_bf16 v[106:109], v[166:169], v[208:211], v[106:109]
	v_mfma_f32_16x16x32_bf16 v[98:101], v[174:177], v[208:211], v[98:101]
	v_mfma_f32_16x16x32_bf16 v[90:93], v[166:169], v[220:223], v[90:93]
	v_mfma_f32_16x16x32_bf16 v[82:85], v[174:177], v[220:223], v[82:85]
	v_mfma_f32_16x16x32_bf16 v[74:77], v[166:169], v[228:231], v[74:77]
	v_mfma_f32_16x16x32_bf16 v[66:69], v[174:177], v[228:231], v[66:69]
	s_barrier
	s_setprio 0
	s_add_i32 s67, s67, s4
	s_mov_b32 m0, s67
	ds_read_b128 v[178:181], v145 offset:16384
	ds_read_b128 v[182:185], v145 offset:17408
	ds_read_b128 v[204:207], v145 offset:18432
	ds_read_b128 v[208:211], v145 offset:19456
	ds_read_b128 v[212:215], v145 offset:20480
	ds_read_b128 v[220:223], v145 offset:21504
	ds_read_b128 v[224:227], v145 offset:22528
	ds_read_b128 v[228:231], v145 offset:23552
	global_load_lds_dwordx4 v134, s[52:53]
	s_add_i32 m0, s67, 0x2000
	s_add_u32 s68, s52, 0x40000
	s_addc_u32 s69, s53, 0
	s_add_i32 s67, s70, s4
	global_load_lds_dwordx4 v130, s[52:53]
	s_mov_b32 m0, s67
	s_nop 0
	global_load_lds_dwordx4 v134, s[68:69]
	s_add_i32 m0, s67, 0x2000
	s_nop 0
	global_load_lds_dwordx4 v130, s[68:69]
	s_mov_b32 m0, s5
	s_nop 0
	global_load_lds_dwordx4 v136, s[54:55]
	s_mov_b32 m0, s6
	s_nop 0
	global_load_lds_dwordx4 v132, s[54:55]
	s_waitcnt vmcnt(8)
	s_waitcnt lgkmcnt(0)
	s_setprio 1
	s_barrier
	v_mfma_f32_16x16x32_bf16 v[62:65], v[146:149], v[178:181], 0
	v_mfma_f32_16x16x32_bf16 v[54:57], v[154:157], v[178:181], 0
	v_mfma_f32_16x16x32_bf16 v[46:49], v[146:149], v[204:207], 0
	v_mfma_f32_16x16x32_bf16 v[38:41], v[154:157], v[204:207], 0
	v_mfma_f32_16x16x32_bf16 v[30:33], v[146:149], v[212:215], 0
	v_mfma_f32_16x16x32_bf16 v[22:25], v[154:157], v[212:215], 0
	v_mfma_f32_16x16x32_bf16 v[14:17], v[146:149], v[224:227], 0
	v_mfma_f32_16x16x32_bf16 v[6:9], v[154:157], v[224:227], 0
	v_mfma_f32_16x16x32_bf16 v[62:65], v[150:153], v[182:185], v[62:65]
	v_mfma_f32_16x16x32_bf16 v[54:57], v[158:161], v[182:185], v[54:57]
	v_mfma_f32_16x16x32_bf16 v[46:49], v[150:153], v[208:211], v[46:49]
	v_mfma_f32_16x16x32_bf16 v[38:41], v[158:161], v[208:211], v[38:41]
	v_mfma_f32_16x16x32_bf16 v[30:33], v[150:153], v[220:223], v[30:33]
	v_mfma_f32_16x16x32_bf16 v[22:25], v[158:161], v[220:223], v[22:25]
	v_mfma_f32_16x16x32_bf16 v[14:17], v[150:153], v[228:231], v[14:17]
	v_mfma_f32_16x16x32_bf16 v[6:9], v[158:161], v[228:231], v[6:9]
	v_mfma_f32_16x16x32_bf16 v[58:61], v[162:165], v[178:181], 0
	v_mfma_f32_16x16x32_bf16 v[50:53], v[170:173], v[178:181], 0
	v_mfma_f32_16x16x32_bf16 v[42:45], v[162:165], v[204:207], 0
	v_mfma_f32_16x16x32_bf16 v[34:37], v[170:173], v[204:207], 0
	v_mfma_f32_16x16x32_bf16 v[26:29], v[162:165], v[212:215], 0
	v_mfma_f32_16x16x32_bf16 v[18:21], v[170:173], v[212:215], 0
	v_mfma_f32_16x16x32_bf16 v[10:13], v[162:165], v[224:227], 0
	v_mfma_f32_16x16x32_bf16 v[2:5], v[170:173], v[224:227], 0
	v_mfma_f32_16x16x32_bf16 v[58:61], v[166:169], v[182:185], v[58:61]
	v_mfma_f32_16x16x32_bf16 v[50:53], v[174:177], v[182:185], v[50:53]
	v_mfma_f32_16x16x32_bf16 v[42:45], v[166:169], v[208:211], v[42:45]
	v_mfma_f32_16x16x32_bf16 v[34:37], v[174:177], v[208:211], v[34:37]
	v_mfma_f32_16x16x32_bf16 v[26:29], v[166:169], v[220:223], v[26:29]
	v_mfma_f32_16x16x32_bf16 v[18:21], v[174:177], v[220:223], v[18:21]
	v_mfma_f32_16x16x32_bf16 v[10:13], v[166:169], v[228:231], v[10:13]
	v_mfma_f32_16x16x32_bf16 v[2:5], v[174:177], v[228:231], v[2:5]
	s_barrier
	s_setprio 0
	s_add_i32 s67, 0, 0x18000
	v_add_u32_e32 v0, s67, v144
	s_add_i32 s68, 0, 0x1c000
	ds_read_b128 v[146:149], v0
	ds_read_b128 v[150:153], v0 offset:1024
	ds_read_b128 v[154:157], v0 offset:2048
	ds_read_b128 v[158:161], v0 offset:3072
	v_add_u32_e32 v0, s68, v144
	ds_read_b128 v[162:165], v0
	ds_read_b128 v[166:169], v0 offset:1024
	ds_read_b128 v[170:173], v0 offset:2048
	ds_read_b128 v[174:177], v0 offset:3072
	s_add_u32 s54, s54, 0x40000
	s_addc_u32 s55, s55, 0
	s_mov_b32 m0, s7
	ds_read_b128 v[178:181], v145 offset:32768
	ds_read_b128 v[182:185], v145 offset:33792
	ds_read_b128 v[204:207], v145 offset:34816
	ds_read_b128 v[208:211], v145 offset:35840
	ds_read_b128 v[212:215], v145 offset:36864
	ds_read_b128 v[220:223], v145 offset:37888
	ds_read_b128 v[224:227], v145 offset:38912
	ds_read_b128 v[228:231], v145 offset:39936
	global_load_lds_dwordx4 v136, s[54:55]
	s_mov_b32 m0, s56
	s_nop 0
	global_load_lds_dwordx4 v132, s[54:55]
	s_waitcnt vmcnt(8)
	s_waitcnt lgkmcnt(0)
	s_setprio 1
	s_barrier
	v_mfma_f32_16x16x32_bf16 v[118:121], v[146:149], v[178:181], v[118:121]
	v_mfma_f32_16x16x32_bf16 v[114:117], v[154:157], v[178:181], v[114:117]
	v_mfma_f32_16x16x32_bf16 v[110:113], v[146:149], v[204:207], v[110:113]
	v_mfma_f32_16x16x32_bf16 v[102:105], v[154:157], v[204:207], v[102:105]
	v_mfma_f32_16x16x32_bf16 v[94:97], v[146:149], v[212:215], v[94:97]
	v_mfma_f32_16x16x32_bf16 v[86:89], v[154:157], v[212:215], v[86:89]
	v_mfma_f32_16x16x32_bf16 v[78:81], v[146:149], v[224:227], v[78:81]
	v_mfma_f32_16x16x32_bf16 v[70:73], v[154:157], v[224:227], v[70:73]
	v_mfma_f32_16x16x32_bf16 v[118:121], v[150:153], v[182:185], v[118:121]
	v_mfma_f32_16x16x32_bf16 v[114:117], v[158:161], v[182:185], v[114:117]
	v_mfma_f32_16x16x32_bf16 v[110:113], v[150:153], v[208:211], v[110:113]
	v_mfma_f32_16x16x32_bf16 v[102:105], v[158:161], v[208:211], v[102:105]
	v_mfma_f32_16x16x32_bf16 v[94:97], v[150:153], v[220:223], v[94:97]
	v_mfma_f32_16x16x32_bf16 v[86:89], v[158:161], v[220:223], v[86:89]
	v_mfma_f32_16x16x32_bf16 v[78:81], v[150:153], v[228:231], v[78:81]
	v_mfma_f32_16x16x32_bf16 v[70:73], v[158:161], v[228:231], v[70:73]
	v_mfma_f32_16x16x32_bf16 v[126:129], v[162:165], v[178:181], v[126:129]
	v_mfma_f32_16x16x32_bf16 v[122:125], v[170:173], v[178:181], v[122:125]
	v_mfma_f32_16x16x32_bf16 v[106:109], v[162:165], v[204:207], v[106:109]
	v_mfma_f32_16x16x32_bf16 v[98:101], v[170:173], v[204:207], v[98:101]
	v_mfma_f32_16x16x32_bf16 v[90:93], v[162:165], v[212:215], v[90:93]
	v_mfma_f32_16x16x32_bf16 v[82:85], v[170:173], v[212:215], v[82:85]
	v_mfma_f32_16x16x32_bf16 v[74:77], v[162:165], v[224:227], v[74:77]
	v_mfma_f32_16x16x32_bf16 v[66:69], v[170:173], v[224:227], v[66:69]
	v_mfma_f32_16x16x32_bf16 v[126:129], v[166:169], v[182:185], v[126:129]
	v_mfma_f32_16x16x32_bf16 v[122:125], v[174:177], v[182:185], v[122:125]
	v_mfma_f32_16x16x32_bf16 v[106:109], v[166:169], v[208:211], v[106:109]
	v_mfma_f32_16x16x32_bf16 v[98:101], v[174:177], v[208:211], v[98:101]
	v_mfma_f32_16x16x32_bf16 v[90:93], v[166:169], v[220:223], v[90:93]
	v_mfma_f32_16x16x32_bf16 v[82:85], v[174:177], v[220:223], v[82:85]
	v_mfma_f32_16x16x32_bf16 v[74:77], v[166:169], v[228:231], v[74:77]
	v_mfma_f32_16x16x32_bf16 v[66:69], v[174:177], v[228:231], v[66:69]
	s_barrier
	s_setprio 0
	s_add_i32 s69, s67, s4
	s_add_u32 s52, s52, 0x80
	s_addc_u32 s53, s53, 0
	s_mov_b32 m0, s69
	ds_read_b128 v[178:181], v145 offset:49152
	ds_read_b128 v[182:185], v145 offset:50176
	ds_read_b128 v[204:207], v145 offset:51200
	ds_read_b128 v[208:211], v145 offset:52224
	ds_read_b128 v[212:215], v145 offset:53248
	ds_read_b128 v[220:223], v145 offset:54272
	ds_read_b128 v[224:227], v145 offset:55296
	ds_read_b128 v[228:231], v145 offset:56320
	global_load_lds_dwordx4 v134, s[52:53]
	s_add_i32 m0, s69, 0x2000
	s_add_i32 s69, s68, s4
	global_load_lds_dwordx4 v130, s[52:53]
	s_add_u32 s52, s52, 0x40000
	s_addc_u32 s53, s53, 0
	s_mov_b32 m0, s69
	s_sub_u32 s54, s54, 0x3ff80
	global_load_lds_dwordx4 v134, s[52:53]
	s_subb_u32 s55, s55, 0
	s_add_i32 m0, s69, 0x2000
	s_nop 0
	global_load_lds_dwordx4 v130, s[52:53]
	s_mov_b32 m0, s59
	s_nop 0
	global_load_lds_dwordx4 v136, s[54:55]
	s_mov_b32 m0, s60
	s_nop 0
	global_load_lds_dwordx4 v132, s[54:55]
	s_waitcnt vmcnt(8)
	s_waitcnt lgkmcnt(0)
	s_setprio 1
	s_barrier
	v_mfma_f32_16x16x32_bf16 v[62:65], v[146:149], v[178:181], v[62:65]
	v_mfma_f32_16x16x32_bf16 v[54:57], v[154:157], v[178:181], v[54:57]
	v_mfma_f32_16x16x32_bf16 v[46:49], v[146:149], v[204:207], v[46:49]
	v_mfma_f32_16x16x32_bf16 v[38:41], v[154:157], v[204:207], v[38:41]
	v_mfma_f32_16x16x32_bf16 v[30:33], v[146:149], v[212:215], v[30:33]
	v_mfma_f32_16x16x32_bf16 v[22:25], v[154:157], v[212:215], v[22:25]
	v_mfma_f32_16x16x32_bf16 v[14:17], v[146:149], v[224:227], v[14:17]
	v_mfma_f32_16x16x32_bf16 v[6:9], v[154:157], v[224:227], v[6:9]
	v_mfma_f32_16x16x32_bf16 v[62:65], v[150:153], v[182:185], v[62:65]
	v_mfma_f32_16x16x32_bf16 v[54:57], v[158:161], v[182:185], v[54:57]
	v_mfma_f32_16x16x32_bf16 v[46:49], v[150:153], v[208:211], v[46:49]
	v_mfma_f32_16x16x32_bf16 v[38:41], v[158:161], v[208:211], v[38:41]
	v_mfma_f32_16x16x32_bf16 v[30:33], v[150:153], v[220:223], v[30:33]
	v_mfma_f32_16x16x32_bf16 v[22:25], v[158:161], v[220:223], v[22:25]
	v_mfma_f32_16x16x32_bf16 v[14:17], v[150:153], v[228:231], v[14:17]
	v_mfma_f32_16x16x32_bf16 v[6:9], v[158:161], v[228:231], v[6:9]
	v_mfma_f32_16x16x32_bf16 v[58:61], v[162:165], v[178:181], v[58:61]
	v_mfma_f32_16x16x32_bf16 v[50:53], v[170:173], v[178:181], v[50:53]
	v_mfma_f32_16x16x32_bf16 v[42:45], v[162:165], v[204:207], v[42:45]
	v_mfma_f32_16x16x32_bf16 v[34:37], v[170:173], v[204:207], v[34:37]
	v_mfma_f32_16x16x32_bf16 v[26:29], v[162:165], v[212:215], v[26:29]
	v_mfma_f32_16x16x32_bf16 v[18:21], v[170:173], v[212:215], v[18:21]
	v_mfma_f32_16x16x32_bf16 v[10:13], v[162:165], v[224:227], v[10:13]
	v_mfma_f32_16x16x32_bf16 v[2:5], v[170:173], v[224:227], v[2:5]
	v_mfma_f32_16x16x32_bf16 v[58:61], v[166:169], v[182:185], v[58:61]
	v_mfma_f32_16x16x32_bf16 v[50:53], v[174:177], v[182:185], v[50:53]
	v_mfma_f32_16x16x32_bf16 v[42:45], v[166:169], v[208:211], v[42:45]
	v_mfma_f32_16x16x32_bf16 v[34:37], v[174:177], v[208:211], v[34:37]
	v_mfma_f32_16x16x32_bf16 v[26:29], v[166:169], v[220:223], v[26:29]
	v_mfma_f32_16x16x32_bf16 v[18:21], v[174:177], v[220:223], v[18:21]
	v_mfma_f32_16x16x32_bf16 v[10:13], v[166:169], v[228:231], v[10:13]
	v_mfma_f32_16x16x32_bf16 v[2:5], v[174:177], v[228:231], v[2:5]
	s_barrier
	s_setprio 0
	s_add_i32 s66, s66, 2
	s_add_u32 s50, s50, 0x100
	s_addc_u32 s51, s51, 0
	s_add_u32 s64, s64, 0x100
	s_addc_u32 s65, s65, 0
	s_cmp_gt_u32 s66, 13
.LBB0_997:
	s_add_u32 s52, s50, 0xfffc0080
	s_addc_u32 s53, s51, -1
	s_add_i32 s67, 0, 0x10000
	s_cmp_eq_u32 s66, 12
	s_cselect_b32 s55, s45, s53
	s_cselect_b32 s54, s62, s52
	v_add_u32_e32 v0, s67, v144
	s_cselect_b32 s53, s43, s65
	s_cselect_b32 s52, s63, s64
	s_add_i32 s70, 0, 0x14000
	ds_read_b128 v[146:149], v0
	ds_read_b128 v[150:153], v0 offset:1024
	ds_read_b128 v[154:157], v0 offset:2048
	ds_read_b128 v[158:161], v0 offset:3072
	v_add_u32_e32 v0, s70, v144
	ds_read_b128 v[162:165], v0
	ds_read_b128 v[166:169], v0 offset:1024
	ds_read_b128 v[170:173], v0 offset:2048
	ds_read_b128 v[174:177], v0 offset:3072
	s_add_i32 m0, s5, 0xc000
	ds_read_b128 v[178:181], v145
	ds_read_b128 v[182:185], v145 offset:1024
	ds_read_b128 v[204:207], v145 offset:2048
	ds_read_b128 v[208:211], v145 offset:3072
	ds_read_b128 v[212:215], v145 offset:4096
	ds_read_b128 v[220:223], v145 offset:5120
	ds_read_b128 v[224:227], v145 offset:6144
	ds_read_b128 v[228:231], v145 offset:7168
	global_load_lds_dwordx4 v138, s[50:51]
	s_add_i32 m0, s5, 0xe000
	s_nop 0
	global_load_lds_dwordx4 v140, s[50:51]
	s_waitcnt vmcnt(8)
	s_waitcnt lgkmcnt(0)
	s_setprio 1
	s_barrier
	v_mfma_f32_16x16x32_bf16 v[118:121], v[146:149], v[178:181], v[118:121]
	v_mfma_f32_16x16x32_bf16 v[114:117], v[154:157], v[178:181], v[114:117]
	v_mfma_f32_16x16x32_bf16 v[110:113], v[146:149], v[204:207], v[110:113]
	v_mfma_f32_16x16x32_bf16 v[102:105], v[154:157], v[204:207], v[102:105]
	v_mfma_f32_16x16x32_bf16 v[94:97], v[146:149], v[212:215], v[94:97]
	v_mfma_f32_16x16x32_bf16 v[86:89], v[154:157], v[212:215], v[86:89]
	v_mfma_f32_16x16x32_bf16 v[78:81], v[146:149], v[224:227], v[78:81]
	v_mfma_f32_16x16x32_bf16 v[70:73], v[154:157], v[224:227], v[70:73]
	v_mfma_f32_16x16x32_bf16 v[118:121], v[150:153], v[182:185], v[118:121]
	v_mfma_f32_16x16x32_bf16 v[114:117], v[158:161], v[182:185], v[114:117]
	v_mfma_f32_16x16x32_bf16 v[110:113], v[150:153], v[208:211], v[110:113]
	v_mfma_f32_16x16x32_bf16 v[102:105], v[158:161], v[208:211], v[102:105]
	v_mfma_f32_16x16x32_bf16 v[94:97], v[150:153], v[220:223], v[94:97]
	v_mfma_f32_16x16x32_bf16 v[86:89], v[158:161], v[220:223], v[86:89]
	v_mfma_f32_16x16x32_bf16 v[78:81], v[150:153], v[228:231], v[78:81]
	v_mfma_f32_16x16x32_bf16 v[70:73], v[158:161], v[228:231], v[70:73]
	v_mfma_f32_16x16x32_bf16 v[126:129], v[162:165], v[178:181], v[126:129]
	v_mfma_f32_16x16x32_bf16 v[122:125], v[170:173], v[178:181], v[122:125]
	v_mfma_f32_16x16x32_bf16 v[106:109], v[162:165], v[204:207], v[106:109]
	v_mfma_f32_16x16x32_bf16 v[98:101], v[170:173], v[204:207], v[98:101]
	v_mfma_f32_16x16x32_bf16 v[90:93], v[162:165], v[212:215], v[90:93]
	v_mfma_f32_16x16x32_bf16 v[82:85], v[170:173], v[212:215], v[82:85]
	v_mfma_f32_16x16x32_bf16 v[74:77], v[162:165], v[224:227], v[74:77]
	v_mfma_f32_16x16x32_bf16 v[66:69], v[170:173], v[224:227], v[66:69]
	v_mfma_f32_16x16x32_bf16 v[126:129], v[166:169], v[182:185], v[126:129]
	v_mfma_f32_16x16x32_bf16 v[122:125], v[174:177], v[182:185], v[122:125]
	v_mfma_f32_16x16x32_bf16 v[106:109], v[166:169], v[208:211], v[106:109]
	v_mfma_f32_16x16x32_bf16 v[98:101], v[174:177], v[208:211], v[98:101]
	v_mfma_f32_16x16x32_bf16 v[90:93], v[166:169], v[220:223], v[90:93]
	v_mfma_f32_16x16x32_bf16 v[82:85], v[174:177], v[220:223], v[82:85]
	v_mfma_f32_16x16x32_bf16 v[74:77], v[166:169], v[228:231], v[74:77]
	v_mfma_f32_16x16x32_bf16 v[66:69], v[174:177], v[228:231], v[66:69]
	s_barrier
	s_setprio 0
	s_add_i32 s67, s67, s4
	s_mov_b32 m0, s67
	ds_read_b128 v[178:181], v145 offset:16384
	ds_read_b128 v[182:185], v145 offset:17408
	ds_read_b128 v[204:207], v145 offset:18432
	ds_read_b128 v[208:211], v145 offset:19456
	ds_read_b128 v[212:215], v145 offset:20480
	ds_read_b128 v[220:223], v145 offset:21504
	ds_read_b128 v[224:227], v145 offset:22528
	ds_read_b128 v[228:231], v145 offset:23552
	global_load_lds_dwordx4 v134, s[52:53]
	s_add_i32 m0, s67, 0x2000
	s_add_u32 s68, s52, 0x40000
	s_addc_u32 s69, s53, 0
	s_add_i32 s67, s70, s4
	global_load_lds_dwordx4 v130, s[52:53]
	s_mov_b32 m0, s67
	s_nop 0
	global_load_lds_dwordx4 v134, s[68:69]
	s_add_i32 m0, s67, 0x2000
	s_nop 0
	global_load_lds_dwordx4 v130, s[68:69]
	s_mov_b32 m0, s5
	s_nop 0
	global_load_lds_dwordx4 v136, s[54:55]
	s_mov_b32 m0, s6
	s_nop 0
	global_load_lds_dwordx4 v132, s[54:55]
	s_waitcnt vmcnt(8)
	s_waitcnt lgkmcnt(0)
	s_setprio 1
	s_barrier
	v_mfma_f32_16x16x32_bf16 v[62:65], v[146:149], v[178:181], v[62:65]
	v_mfma_f32_16x16x32_bf16 v[54:57], v[154:157], v[178:181], v[54:57]
	v_mfma_f32_16x16x32_bf16 v[46:49], v[146:149], v[204:207], v[46:49]
	v_mfma_f32_16x16x32_bf16 v[38:41], v[154:157], v[204:207], v[38:41]
	v_mfma_f32_16x16x32_bf16 v[30:33], v[146:149], v[212:215], v[30:33]
	v_mfma_f32_16x16x32_bf16 v[22:25], v[154:157], v[212:215], v[22:25]
	v_mfma_f32_16x16x32_bf16 v[14:17], v[146:149], v[224:227], v[14:17]
	v_mfma_f32_16x16x32_bf16 v[6:9], v[154:157], v[224:227], v[6:9]
	v_mfma_f32_16x16x32_bf16 v[62:65], v[150:153], v[182:185], v[62:65]
	v_mfma_f32_16x16x32_bf16 v[54:57], v[158:161], v[182:185], v[54:57]
	v_mfma_f32_16x16x32_bf16 v[46:49], v[150:153], v[208:211], v[46:49]
	v_mfma_f32_16x16x32_bf16 v[38:41], v[158:161], v[208:211], v[38:41]
	v_mfma_f32_16x16x32_bf16 v[30:33], v[150:153], v[220:223], v[30:33]
	v_mfma_f32_16x16x32_bf16 v[22:25], v[158:161], v[220:223], v[22:25]
	v_mfma_f32_16x16x32_bf16 v[14:17], v[150:153], v[228:231], v[14:17]
	v_mfma_f32_16x16x32_bf16 v[6:9], v[158:161], v[228:231], v[6:9]
	v_mfma_f32_16x16x32_bf16 v[58:61], v[162:165], v[178:181], v[58:61]
	v_mfma_f32_16x16x32_bf16 v[50:53], v[170:173], v[178:181], v[50:53]
	v_mfma_f32_16x16x32_bf16 v[42:45], v[162:165], v[204:207], v[42:45]
	v_mfma_f32_16x16x32_bf16 v[34:37], v[170:173], v[204:207], v[34:37]
	v_mfma_f32_16x16x32_bf16 v[26:29], v[162:165], v[212:215], v[26:29]
	v_mfma_f32_16x16x32_bf16 v[18:21], v[170:173], v[212:215], v[18:21]
	v_mfma_f32_16x16x32_bf16 v[10:13], v[162:165], v[224:227], v[10:13]
	v_mfma_f32_16x16x32_bf16 v[2:5], v[170:173], v[224:227], v[2:5]
	v_mfma_f32_16x16x32_bf16 v[58:61], v[166:169], v[182:185], v[58:61]
	v_mfma_f32_16x16x32_bf16 v[50:53], v[174:177], v[182:185], v[50:53]
	v_mfma_f32_16x16x32_bf16 v[42:45], v[166:169], v[208:211], v[42:45]
	v_mfma_f32_16x16x32_bf16 v[34:37], v[174:177], v[208:211], v[34:37]
	v_mfma_f32_16x16x32_bf16 v[26:29], v[166:169], v[220:223], v[26:29]
	v_mfma_f32_16x16x32_bf16 v[18:21], v[174:177], v[220:223], v[18:21]
	v_mfma_f32_16x16x32_bf16 v[10:13], v[166:169], v[228:231], v[10:13]
	v_mfma_f32_16x16x32_bf16 v[2:5], v[174:177], v[228:231], v[2:5]
	s_barrier
	s_setprio 0
	s_add_i32 s67, 0, 0x18000
	v_add_u32_e32 v0, s67, v144
	s_add_i32 s68, 0, 0x1c000
	ds_read_b128 v[146:149], v0
	ds_read_b128 v[150:153], v0 offset:1024
	ds_read_b128 v[154:157], v0 offset:2048
	ds_read_b128 v[158:161], v0 offset:3072
	v_add_u32_e32 v0, s68, v144
	ds_read_b128 v[162:165], v0
	ds_read_b128 v[166:169], v0 offset:1024
	ds_read_b128 v[170:173], v0 offset:2048
	ds_read_b128 v[174:177], v0 offset:3072
	s_add_u32 s54, s54, 0x40000
	s_addc_u32 s55, s55, 0
	s_mov_b32 m0, s7
	ds_read_b128 v[178:181], v145 offset:32768
	ds_read_b128 v[182:185], v145 offset:33792
	ds_read_b128 v[204:207], v145 offset:34816
	ds_read_b128 v[208:211], v145 offset:35840
	ds_read_b128 v[212:215], v145 offset:36864
	ds_read_b128 v[220:223], v145 offset:37888
	ds_read_b128 v[224:227], v145 offset:38912
	ds_read_b128 v[228:231], v145 offset:39936
	global_load_lds_dwordx4 v136, s[54:55]
	s_mov_b32 m0, s56
	s_nop 0
	global_load_lds_dwordx4 v132, s[54:55]
	s_waitcnt vmcnt(8)
	s_waitcnt lgkmcnt(0)
	s_setprio 1
	s_barrier
	v_mfma_f32_16x16x32_bf16 v[118:121], v[146:149], v[178:181], v[118:121]
	v_mfma_f32_16x16x32_bf16 v[114:117], v[154:157], v[178:181], v[114:117]
	v_mfma_f32_16x16x32_bf16 v[110:113], v[146:149], v[204:207], v[110:113]
	v_mfma_f32_16x16x32_bf16 v[102:105], v[154:157], v[204:207], v[102:105]
	v_mfma_f32_16x16x32_bf16 v[94:97], v[146:149], v[212:215], v[94:97]
	v_mfma_f32_16x16x32_bf16 v[86:89], v[154:157], v[212:215], v[86:89]
	v_mfma_f32_16x16x32_bf16 v[78:81], v[146:149], v[224:227], v[78:81]
	v_mfma_f32_16x16x32_bf16 v[70:73], v[154:157], v[224:227], v[70:73]
	v_mfma_f32_16x16x32_bf16 v[118:121], v[150:153], v[182:185], v[118:121]
	v_mfma_f32_16x16x32_bf16 v[114:117], v[158:161], v[182:185], v[114:117]
	v_mfma_f32_16x16x32_bf16 v[110:113], v[150:153], v[208:211], v[110:113]
	v_mfma_f32_16x16x32_bf16 v[102:105], v[158:161], v[208:211], v[102:105]
	v_mfma_f32_16x16x32_bf16 v[94:97], v[150:153], v[220:223], v[94:97]
	v_mfma_f32_16x16x32_bf16 v[86:89], v[158:161], v[220:223], v[86:89]
	v_mfma_f32_16x16x32_bf16 v[78:81], v[150:153], v[228:231], v[78:81]
	v_mfma_f32_16x16x32_bf16 v[70:73], v[158:161], v[228:231], v[70:73]
	v_mfma_f32_16x16x32_bf16 v[126:129], v[162:165], v[178:181], v[126:129]
	v_mfma_f32_16x16x32_bf16 v[122:125], v[170:173], v[178:181], v[122:125]
	v_mfma_f32_16x16x32_bf16 v[106:109], v[162:165], v[204:207], v[106:109]
	v_mfma_f32_16x16x32_bf16 v[98:101], v[170:173], v[204:207], v[98:101]
	v_mfma_f32_16x16x32_bf16 v[90:93], v[162:165], v[212:215], v[90:93]
	v_mfma_f32_16x16x32_bf16 v[82:85], v[170:173], v[212:215], v[82:85]
	v_mfma_f32_16x16x32_bf16 v[74:77], v[162:165], v[224:227], v[74:77]
	v_mfma_f32_16x16x32_bf16 v[66:69], v[170:173], v[224:227], v[66:69]
	v_mfma_f32_16x16x32_bf16 v[126:129], v[166:169], v[182:185], v[126:129]
	v_mfma_f32_16x16x32_bf16 v[122:125], v[174:177], v[182:185], v[122:125]
	v_mfma_f32_16x16x32_bf16 v[106:109], v[166:169], v[208:211], v[106:109]
	v_mfma_f32_16x16x32_bf16 v[98:101], v[174:177], v[208:211], v[98:101]
	v_mfma_f32_16x16x32_bf16 v[90:93], v[166:169], v[220:223], v[90:93]
	v_mfma_f32_16x16x32_bf16 v[82:85], v[174:177], v[220:223], v[82:85]
	v_mfma_f32_16x16x32_bf16 v[74:77], v[166:169], v[228:231], v[74:77]
	v_mfma_f32_16x16x32_bf16 v[66:69], v[174:177], v[228:231], v[66:69]
	s_barrier
	s_setprio 0
	s_add_i32 s69, s67, s4
	s_add_u32 s52, s52, 0x80
	s_addc_u32 s53, s53, 0
	s_mov_b32 m0, s69
	ds_read_b128 v[178:181], v145 offset:49152
	ds_read_b128 v[182:185], v145 offset:50176
	ds_read_b128 v[204:207], v145 offset:51200
	ds_read_b128 v[208:211], v145 offset:52224
	ds_read_b128 v[212:215], v145 offset:53248
	ds_read_b128 v[220:223], v145 offset:54272
	ds_read_b128 v[224:227], v145 offset:55296
	ds_read_b128 v[228:231], v145 offset:56320
	global_load_lds_dwordx4 v134, s[52:53]
	s_add_i32 m0, s69, 0x2000
	s_add_i32 s69, s68, s4
	global_load_lds_dwordx4 v130, s[52:53]
	s_add_u32 s52, s52, 0x40000
	s_addc_u32 s53, s53, 0
	s_mov_b32 m0, s69
	s_sub_u32 s54, s54, 0x3ff80
	global_load_lds_dwordx4 v134, s[52:53]
	s_subb_u32 s55, s55, 0
	s_add_i32 m0, s69, 0x2000
	s_nop 0
	global_load_lds_dwordx4 v130, s[52:53]
	s_mov_b32 m0, s59
	s_nop 0
	global_load_lds_dwordx4 v136, s[54:55]
	s_mov_b32 m0, s60
	s_nop 0
	global_load_lds_dwordx4 v132, s[54:55]
	s_waitcnt vmcnt(8)
	s_waitcnt lgkmcnt(0)
	s_setprio 1
	s_barrier
	v_mfma_f32_16x16x32_bf16 v[62:65], v[146:149], v[178:181], v[62:65]
	v_mfma_f32_16x16x32_bf16 v[54:57], v[154:157], v[178:181], v[54:57]
	v_mfma_f32_16x16x32_bf16 v[46:49], v[146:149], v[204:207], v[46:49]
	v_mfma_f32_16x16x32_bf16 v[38:41], v[154:157], v[204:207], v[38:41]
	v_mfma_f32_16x16x32_bf16 v[30:33], v[146:149], v[212:215], v[30:33]
	v_mfma_f32_16x16x32_bf16 v[22:25], v[154:157], v[212:215], v[22:25]
	v_mfma_f32_16x16x32_bf16 v[14:17], v[146:149], v[224:227], v[14:17]
	v_mfma_f32_16x16x32_bf16 v[6:9], v[154:157], v[224:227], v[6:9]
	v_mfma_f32_16x16x32_bf16 v[62:65], v[150:153], v[182:185], v[62:65]
	v_mfma_f32_16x16x32_bf16 v[54:57], v[158:161], v[182:185], v[54:57]
	v_mfma_f32_16x16x32_bf16 v[46:49], v[150:153], v[208:211], v[46:49]
	v_mfma_f32_16x16x32_bf16 v[38:41], v[158:161], v[208:211], v[38:41]
	v_mfma_f32_16x16x32_bf16 v[30:33], v[150:153], v[220:223], v[30:33]
	v_mfma_f32_16x16x32_bf16 v[22:25], v[158:161], v[220:223], v[22:25]
	v_mfma_f32_16x16x32_bf16 v[14:17], v[150:153], v[228:231], v[14:17]
	v_mfma_f32_16x16x32_bf16 v[6:9], v[158:161], v[228:231], v[6:9]
	v_mfma_f32_16x16x32_bf16 v[58:61], v[162:165], v[178:181], v[58:61]
	v_mfma_f32_16x16x32_bf16 v[50:53], v[170:173], v[178:181], v[50:53]
	v_mfma_f32_16x16x32_bf16 v[42:45], v[162:165], v[204:207], v[42:45]
	v_mfma_f32_16x16x32_bf16 v[34:37], v[170:173], v[204:207], v[34:37]
	v_mfma_f32_16x16x32_bf16 v[26:29], v[162:165], v[212:215], v[26:29]
	v_mfma_f32_16x16x32_bf16 v[18:21], v[170:173], v[212:215], v[18:21]
	v_mfma_f32_16x16x32_bf16 v[10:13], v[162:165], v[224:227], v[10:13]
	v_mfma_f32_16x16x32_bf16 v[2:5], v[170:173], v[224:227], v[2:5]
	v_mfma_f32_16x16x32_bf16 v[58:61], v[166:169], v[182:185], v[58:61]
	v_mfma_f32_16x16x32_bf16 v[50:53], v[174:177], v[182:185], v[50:53]
	v_mfma_f32_16x16x32_bf16 v[42:45], v[166:169], v[208:211], v[42:45]
	v_mfma_f32_16x16x32_bf16 v[34:37], v[174:177], v[208:211], v[34:37]
	v_mfma_f32_16x16x32_bf16 v[26:29], v[166:169], v[220:223], v[26:29]
	v_mfma_f32_16x16x32_bf16 v[18:21], v[174:177], v[220:223], v[18:21]
	v_mfma_f32_16x16x32_bf16 v[10:13], v[166:169], v[228:231], v[10:13]
	v_mfma_f32_16x16x32_bf16 v[2:5], v[174:177], v[228:231], v[2:5]
	s_barrier
	s_setprio 0
	s_add_i32 s66, s66, 2
	s_add_u32 s50, s50, 0x100
	s_addc_u32 s51, s51, 0
	s_add_u32 s64, s64, 0x100
	s_addc_u32 s65, s65, 0
	s_cmp_gt_u32 s66, 13
	s_cbranch_scc0 .LBB0_997
	s_and_b64 vcc, exec, s[40:41]
	s_cbranch_vccz .LBB0_1000
	s_barrier
